# write-through (sc0 sc1) on the INA / INB / UQ GEMM epilogue dwordx4 stores (80 stores), on top of v25
# baseline (speedup 1.0000x reference)
.LBB0_993:
	v_lshl_add_u32 v180, s43, 8, v190
	v_ashrrev_i32_e32 v181, 31, v180
	v_lshlrev_b64 v[128:129], 6, v[180:181]
	v_or_b32_e32 v178, 16, v180
	v_lshl_add_u64 v[128:129], v[152:153], 0, v[128:129]
	v_ashrrev_i32_e32 v179, 31, v178
	global_load_dwordx4 v[182:185], v[128:129], off
	v_lshlrev_b64 v[128:129], 6, v[178:179]
	v_lshl_add_u64 v[128:129], v[152:153], 0, v[128:129]
	global_load_dwordx4 v[186:189], v[128:129], off
	v_or_b32_e32 v176, 32, v180
	v_ashrrev_i32_e32 v177, 31, v176
	v_lshlrev_b64 v[128:129], 6, v[176:177]
	v_or_b32_e32 v174, 48, v180
	v_lshl_add_u64 v[128:129], v[152:153], 0, v[128:129]
	v_ashrrev_i32_e32 v175, 31, v174
	global_load_dwordx4 v[196:199], v[128:129], off
	v_lshlrev_b64 v[128:129], 6, v[174:175]
	v_add_u32_e32 v172, 0x80, v180
	v_lshl_add_u64 v[128:129], v[152:153], 0, v[128:129]
	v_ashrrev_i32_e32 v173, 31, v172
	global_load_dwordx4 v[200:203], v[128:129], off
	v_lshlrev_b64 v[128:129], 6, v[172:173]
	v_add_u32_e32 v170, 0x90, v180
	v_lshl_add_u64 v[128:129], v[152:153], 0, v[128:129]
	v_ashrrev_i32_e32 v171, 31, v170
	global_load_dwordx4 v[136:139], v[128:129], off
	v_lshlrev_b64 v[128:129], 6, v[170:171]
	v_add_u32_e32 v168, 0xa0, v180
	v_lshl_add_u64 v[128:129], v[152:153], 0, v[128:129]
	v_ashrrev_i32_e32 v169, 31, v168
	global_load_dwordx4 v[140:143], v[128:129], off
	v_lshlrev_b64 v[128:129], 6, v[168:169]
	v_add_u32_e32 v166, 0xb0, v180
	v_lshl_add_u64 v[128:129], v[152:153], 0, v[128:129]
	v_ashrrev_i32_e32 v167, 31, v166
	global_load_dwordx4 v[132:135], v[128:129], off
	v_lshlrev_b64 v[128:129], 6, v[166:167]
	v_lshl_add_u64 v[128:129], v[152:153], 0, v[128:129]
	global_load_dwordx4 v[128:131], v[128:129], off
	v_and_b32_e32 v194, 64, v208
	v_xor_b32_e32 v193, 16, v208
	v_add_u32_e32 v194, 64, v194
	v_cmp_lt_i32_e32 vcc, v193, v194
	v_xor_b32_e32 v195, 32, v208
	s_cmp_eq_u32 s42, 0
	v_cndmask_b32_e32 v193, v208, v193, vcc
	v_lshlrev_b32_e32 v193, 2, v193
	v_cmp_lt_i32_e32 vcc, v195, v194
	s_cselect_b64 s[34:35], -1, 0
	s_cmp_lg_u32 s42, 0
	v_cndmask_b32_e32 v194, v208, v195, vcc
	v_lshlrev_b32_e32 v194, 2, v194
	s_cselect_b64 s[36:37], -1, 0
	s_mov_b64 s[4:5], -1
	s_waitcnt vmcnt(0)
	v_mov_b32_e32 v204, v183
	v_mov_b32_e32 v205, v184
	v_mov_b32_e32 v183, v185
	v_mov_b32_e32 v184, v187
	v_mov_b32_e32 v185, v188
	v_mov_b32_e32 v187, v189
	v_pk_add_f32 v[182:183], v[204:205], v[182:183]
	v_pk_add_f32 v[184:185], v[184:185], v[186:187]
	v_mov_b32_e32 v187, v182
	v_mov_b32_e32 v186, v184
	v_mov_b32_e32 v182, v185
	v_pk_add_f32 v[182:183], v[186:187], v[182:183]
	ds_bpermute_b32 v185, v193, v183
	ds_bpermute_b32 v184, v193, v182
	s_waitcnt lgkmcnt(0)
	v_pk_add_f32 v[182:183], v[182:183], v[184:185]
	ds_bpermute_b32 v185, v194, v183
	ds_bpermute_b32 v184, v194, v182
	s_waitcnt lgkmcnt(0)
	v_pk_add_f32 v[182:183], v[182:183], v[184:185]
	s_nop 0
	v_pk_fma_f32 v[186:187], v[182:183], s[86:87], v[162:163] op_sel_hi:[1,0,0]
	v_mov_b32_e32 v184, v201
	v_mul_f32_e32 v182, 0x4b800000, v187
	v_cmp_gt_f32_e32 vcc, s26, v187
	v_mov_b32_e32 v185, v202
	v_mov_b32_e32 v201, v203
	v_cndmask_b32_e32 v182, v187, v182, vcc
	v_rsq_f32_e32 v182, v182
	v_pk_add_f32 v[184:185], v[184:185], v[200:201]
	v_cmp_gt_f32_e64 s[44:45], s26, v186
	v_mul_f32_e32 v183, 0x45800000, v182
	v_cndmask_b32_e32 v188, v182, v183, vcc
	v_mov_b32_e32 v182, v197
	v_mov_b32_e32 v183, v198
	v_mov_b32_e32 v197, v199
	v_pk_add_f32 v[182:183], v[182:183], v[196:197]
	v_mov_b32_e32 v196, v184
	v_mov_b32_e32 v197, v182
	v_mov_b32_e32 v182, v185
	v_pk_add_f32 v[182:183], v[196:197], v[182:183]
	v_mov_b32_e32 v196, v137
	v_mov_b32_e32 v197, v138
	v_mov_b32_e32 v137, v139
	v_mov_b32_e32 v138, v141
	v_mov_b32_e32 v139, v142
	v_mov_b32_e32 v141, v143
	v_pk_add_f32 v[136:137], v[196:197], v[136:137]
	v_pk_add_f32 v[138:139], v[138:139], v[140:141]
	v_mov_b32_e32 v141, v136
	v_mov_b32_e32 v140, v138
	v_mov_b32_e32 v136, v139
	v_pk_add_f32 v[136:137], v[140:141], v[136:137]
	v_mov_b32_e32 v140, v133
	v_mov_b32_e32 v141, v134
	v_mov_b32_e32 v133, v135
	v_mov_b32_e32 v134, v129
	v_mov_b32_e32 v135, v130
	v_mov_b32_e32 v129, v131
	v_pk_add_f32 v[132:133], v[140:141], v[132:133]
	v_pk_add_f32 v[128:129], v[134:135], v[128:129]
	v_mov_b32_e32 v131, v132
	v_mov_b32_e32 v130, v128
	v_mov_b32_e32 v132, v129
	v_pk_add_f32 v[128:129], v[130:131], v[132:133]
	ds_bpermute_b32 v185, v193, v183
	ds_bpermute_b32 v184, v193, v182
	ds_bpermute_b32 v139, v193, v137
	ds_bpermute_b32 v138, v193, v136
	ds_bpermute_b32 v131, v193, v129
	ds_bpermute_b32 v130, v193, v128
	s_waitcnt lgkmcnt(4)
	v_pk_add_f32 v[182:183], v[182:183], v[184:185]
	ds_bpermute_b32 v185, v194, v183
	s_waitcnt lgkmcnt(3)
	v_pk_add_f32 v[136:137], v[136:137], v[138:139]
	ds_bpermute_b32 v184, v194, v182
	s_waitcnt lgkmcnt(2)
	v_pk_add_f32 v[128:129], v[128:129], v[130:131]
	ds_bpermute_b32 v139, v194, v137
	ds_bpermute_b32 v138, v194, v136
	ds_bpermute_b32 v131, v194, v129
	ds_bpermute_b32 v130, v194, v128
	v_lshlrev_b64 v[132:133], 10, v[180:181]
	v_pk_mul_f32 v[126:127], v[126:127], v[188:189] op_sel_hi:[1,0]
	v_pk_mul_f32 v[124:125], v[124:125], v[188:189] op_sel_hi:[1,0]
	v_pk_mul_f32 v[134:135], v[122:123], v[188:189] op_sel_hi:[1,0]
	v_pk_mul_f32 v[122:123], v[120:121], v[188:189] op_sel_hi:[1,0]
	v_cvt_pk_bf16_f32 v120, v124, v125
	v_cvt_pk_bf16_f32 v121, v126, v127
	v_cvt_pk_bf16_f32 v122, v122, v123
	v_cvt_pk_bf16_f32 v123, v134, v135
	s_and_b64 vcc, exec, s[36:37]
	v_lshl_add_u64 v[124:125], v[154:155], 0, v[132:133]
	s_cbranch_vccz .LBB0_995
	global_store_dwordx4 v[124:125], v[120:123], off offset:512 sc0 sc1
	s_mov_b64 s[4:5], 0
.LBB0_995:
	v_lshlrev_b64 v[126:127], 9, v[180:181]
	v_mov_b32_e32 v132, 0
	s_andn2_b64 vcc, exec, s[4:5]
	v_lshl_add_u64 v[126:127], v[150:151], 0, v[126:127]
	s_cbranch_vccnz .LBB0_997
	global_store_dwordx4 v[126:127], v[120:123], off sc0 sc1
	v_lshlrev_b32_e32 v133, 16, v122
	v_and_b32_e32 v135, 0xffff0000, v122
	v_and_b32_e32 v134, 0xffff0000, v120
	v_lshlrev_b32_e32 v141, 16, v123
	v_and_b32_e32 v123, 0xffff0000, v123
	v_and_b32_e32 v122, 0xffff0000, v121
	v_lshlrev_b32_e32 v132, 16, v120
	v_lshlrev_b32_e32 v140, 16, v121
	v_pk_mul_f32 v[120:121], v[134:135], v[134:135]
	v_pk_mul_f32 v[122:123], v[122:123], v[122:123]
	v_pk_fma_f32 v[120:121], v[132:133], v[132:133], v[120:121]
	v_pk_fma_f32 v[122:123], v[140:141], v[140:141], v[122:123]
	s_nop 0
	v_pk_add_f32 v[120:121], v[120:121], v[122:123]
	s_nop 0
	v_add_f32_e32 v132, v120, v121

.LBB0_1000:
	global_store_dwordx4 v[124:125], v[112:115], off offset:768 sc0 sc1
	s_cbranch_execnz .LBB0_999
.LBB0_1001:
	global_store_dwordx4 v[126:127], v[112:115], off offset:256 sc0 sc1
	v_lshlrev_b32_e32 v117, 16, v114
	v_and_b32_e32 v119, 0xffff0000, v114
	v_and_b32_e32 v118, 0xffff0000, v112
	v_lshlrev_b32_e32 v121, 16, v115
	v_and_b32_e32 v115, 0xffff0000, v115
	v_and_b32_e32 v114, 0xffff0000, v113
	v_lshlrev_b32_e32 v116, 16, v112
	v_lshlrev_b32_e32 v120, 16, v113
	v_pk_mul_f32 v[112:113], v[118:119], v[118:119]
	v_pk_mul_f32 v[114:115], v[114:115], v[114:115]
	v_pk_fma_f32 v[112:113], v[116:117], v[116:117], v[112:113]
	v_pk_fma_f32 v[114:115], v[120:121], v[120:121], v[114:115]
	s_nop 0
	v_pk_add_f32 v[112:113], v[112:113], v[114:115]
	s_nop 0
	v_add_f32_e32 v112, v112, v113
	v_add_f32_e32 v132, v112, v132
	v_cndmask_b32_e64 v112, 0, 1, s[34:35]
	v_cmp_ne_u32_e64 s[42:43], 1, v112
	s_andn2_b64 vcc, exec, s[34:35]
	s_cbranch_vccnz .LBB0_1005

.LBB0_1005:
	v_mul_f32_e32 v112, 0x4b800000, v186
	v_cndmask_b32_e64 v112, v186, v112, s[44:45]
	v_rsq_f32_e32 v112, v112
	v_lshlrev_b64 v[114:115], 10, v[178:179]
	s_mov_b64 s[34:35], -1
	s_and_b64 vcc, exec, s[4:5]
	s_waitcnt lgkmcnt(0)
	v_mul_f32_e32 v113, 0x45800000, v112
	v_cndmask_b32_e64 v112, v112, v113, s[44:45]
	v_pk_mul_f32 v[110:111], v[110:111], v[112:113] op_sel_hi:[1,0]
	v_pk_mul_f32 v[108:109], v[108:109], v[112:113] op_sel_hi:[1,0]
	v_pk_mul_f32 v[116:117], v[106:107], v[112:113] op_sel_hi:[1,0]
	v_pk_mul_f32 v[106:107], v[104:105], v[112:113] op_sel_hi:[1,0]
	v_cvt_pk_bf16_f32 v104, v108, v109
	v_cvt_pk_bf16_f32 v105, v110, v111
	v_cvt_pk_bf16_f32 v106, v106, v107
	v_cvt_pk_bf16_f32 v107, v116, v117
	v_lshl_add_u64 v[108:109], v[154:155], 0, v[114:115]
	s_cbranch_vccnz .LBB0_1007
	s_mov_b64 s[34:35], 0
	global_store_dwordx4 v[108:109], v[104:107], off offset:512 sc0 sc1
.LBB0_1007:
	v_lshlrev_b64 v[110:111], 9, v[178:179]
	v_mov_b32_e32 v114, 0
	s_andn2_b64 vcc, exec, s[34:35]
	v_lshl_add_u64 v[110:111], v[150:151], 0, v[110:111]
	s_cbranch_vccnz .LBB0_1009
	global_store_dwordx4 v[110:111], v[104:107], off sc0 sc1
	v_lshlrev_b32_e32 v115, 16, v106
	v_and_b32_e32 v117, 0xffff0000, v106
	v_and_b32_e32 v116, 0xffff0000, v104
	v_lshlrev_b32_e32 v119, 16, v107
	v_and_b32_e32 v107, 0xffff0000, v107
	v_and_b32_e32 v106, 0xffff0000, v105
	v_lshlrev_b32_e32 v114, 16, v104
	v_lshlrev_b32_e32 v118, 16, v105
	v_pk_mul_f32 v[104:105], v[116:117], v[116:117]
	v_pk_mul_f32 v[106:107], v[106:107], v[106:107]
	v_pk_fma_f32 v[104:105], v[114:115], v[114:115], v[104:105]
	v_pk_fma_f32 v[106:107], v[118:119], v[118:119], v[106:107]
	s_nop 0
	v_pk_add_f32 v[104:105], v[104:105], v[106:107]
	s_nop 0
	v_add_f32_e32 v114, v104, v105

.LBB0_1012:
	global_store_dwordx4 v[108:109], v[96:99], off offset:768 sc0 sc1
	s_cbranch_execnz .LBB0_1011
.LBB0_1013:
	global_store_dwordx4 v[110:111], v[96:99], off offset:256 sc0 sc1
	v_lshlrev_b32_e32 v101, 16, v98
	v_and_b32_e32 v103, 0xffff0000, v98
	v_and_b32_e32 v102, 0xffff0000, v96
	v_lshlrev_b32_e32 v105, 16, v99
	v_and_b32_e32 v99, 0xffff0000, v99
	v_and_b32_e32 v98, 0xffff0000, v97
	v_lshlrev_b32_e32 v100, 16, v96
	v_lshlrev_b32_e32 v104, 16, v97
	v_pk_mul_f32 v[96:97], v[102:103], v[102:103]
	v_pk_mul_f32 v[98:99], v[98:99], v[98:99]
	v_pk_fma_f32 v[96:97], v[100:101], v[100:101], v[96:97]
	v_pk_fma_f32 v[98:99], v[104:105], v[104:105], v[98:99]
	s_nop 0
	v_pk_add_f32 v[96:97], v[96:97], v[98:99]
	s_nop 0
	v_add_f32_e32 v96, v96, v97
	v_add_f32_e32 v114, v96, v114
	s_and_b64 vcc, exec, s[42:43]
	s_cbranch_vccnz .LBB0_1017

.LBB0_1017:
	s_waitcnt lgkmcnt(0)
	v_pk_add_f32 v[96:97], v[182:183], v[184:185]
	v_lshlrev_b64 v[100:101], 10, v[176:177]
	v_pk_fma_f32 v[96:97], v[96:97], s[86:87], v[162:163] op_sel_hi:[1,0,0]
	s_mov_b64 s[34:35], -1
	v_mul_f32_e32 v98, 0x4b800000, v97
	v_cmp_gt_f32_e32 vcc, s26, v97
	v_cmp_gt_f32_e64 s[44:45], s26, v96
	s_nop 0
	v_cndmask_b32_e32 v97, v97, v98, vcc
	v_rsq_f32_e32 v97, v97
	s_nop 0
	v_mul_f32_e32 v98, 0x45800000, v97
	v_cndmask_b32_e32 v98, v97, v98, vcc
	v_pk_mul_f32 v[94:95], v[94:95], v[98:99] op_sel_hi:[1,0]
	v_pk_mul_f32 v[92:93], v[92:93], v[98:99] op_sel_hi:[1,0]
	v_pk_mul_f32 v[102:103], v[90:91], v[98:99] op_sel_hi:[1,0]
	v_pk_mul_f32 v[90:91], v[88:89], v[98:99] op_sel_hi:[1,0]
	v_cvt_pk_bf16_f32 v88, v92, v93
	v_cvt_pk_bf16_f32 v89, v94, v95
	v_cvt_pk_bf16_f32 v90, v90, v91
	v_cvt_pk_bf16_f32 v91, v102, v103
	s_and_b64 vcc, exec, s[4:5]
	v_lshl_add_u64 v[92:93], v[154:155], 0, v[100:101]
	s_cbranch_vccnz .LBB0_1019
	s_mov_b64 s[34:35], 0
	global_store_dwordx4 v[92:93], v[88:91], off offset:512 sc0 sc1
.LBB0_1019:
	v_lshlrev_b64 v[94:95], 9, v[176:177]
	v_mov_b32_e32 v97, 0
	s_andn2_b64 vcc, exec, s[34:35]
	v_lshl_add_u64 v[94:95], v[150:151], 0, v[94:95]
	s_cbranch_vccnz .LBB0_1021
	global_store_dwordx4 v[94:95], v[88:91], off sc0 sc1
	v_lshlrev_b32_e32 v101, 16, v90
	v_and_b32_e32 v103, 0xffff0000, v90
	v_and_b32_e32 v102, 0xffff0000, v88
	v_lshlrev_b32_e32 v105, 16, v91
	v_and_b32_e32 v91, 0xffff0000, v91
	v_and_b32_e32 v90, 0xffff0000, v89
	v_lshlrev_b32_e32 v100, 16, v88
	v_lshlrev_b32_e32 v104, 16, v89
	v_pk_mul_f32 v[88:89], v[102:103], v[102:103]
	v_pk_mul_f32 v[90:91], v[90:91], v[90:91]
	v_pk_fma_f32 v[88:89], v[100:101], v[100:101], v[88:89]
	v_pk_fma_f32 v[90:91], v[104:105], v[104:105], v[90:91]
	s_nop 0
	v_pk_add_f32 v[88:89], v[88:89], v[90:91]
	s_nop 0
	v_add_f32_e32 v97, v88, v89

.LBB0_1024:
	global_store_dwordx4 v[92:93], v[80:83], off offset:768 sc0 sc1
	s_cbranch_execnz .LBB0_1023
.LBB0_1025:
	global_store_dwordx4 v[94:95], v[80:83], off offset:256 sc0 sc1
	v_lshlrev_b32_e32 v85, 16, v82
	v_and_b32_e32 v87, 0xffff0000, v82
	v_and_b32_e32 v86, 0xffff0000, v80
	v_lshlrev_b32_e32 v89, 16, v83
	v_and_b32_e32 v83, 0xffff0000, v83
	v_and_b32_e32 v82, 0xffff0000, v81
	v_lshlrev_b32_e32 v84, 16, v80
	v_lshlrev_b32_e32 v88, 16, v81
	v_pk_mul_f32 v[80:81], v[86:87], v[86:87]
	v_pk_mul_f32 v[82:83], v[82:83], v[82:83]
	v_pk_fma_f32 v[80:81], v[84:85], v[84:85], v[80:81]
	v_pk_fma_f32 v[82:83], v[88:89], v[88:89], v[82:83]
	s_nop 0
	v_pk_add_f32 v[80:81], v[80:81], v[82:83]
	s_nop 0
	v_add_f32_e32 v80, v80, v81
	v_add_f32_e32 v97, v80, v97
	s_and_b64 vcc, exec, s[42:43]
	s_cbranch_vccnz .LBB0_1029

.LBB0_1029:
	v_mul_f32_e32 v80, 0x4b800000, v96
	v_cndmask_b32_e64 v80, v96, v80, s[44:45]
	v_rsq_f32_e32 v80, v80
	v_lshlrev_b64 v[82:83], 10, v[174:175]
	s_mov_b64 s[34:35], -1
	s_and_b64 vcc, exec, s[4:5]
	s_waitcnt lgkmcnt(0)
	v_mul_f32_e32 v81, 0x45800000, v80
	v_cndmask_b32_e64 v80, v80, v81, s[44:45]
	v_pk_mul_f32 v[78:79], v[78:79], v[80:81] op_sel_hi:[1,0]
	v_pk_mul_f32 v[76:77], v[76:77], v[80:81] op_sel_hi:[1,0]
	v_pk_mul_f32 v[84:85], v[74:75], v[80:81] op_sel_hi:[1,0]
	v_pk_mul_f32 v[74:75], v[72:73], v[80:81] op_sel_hi:[1,0]
	v_cvt_pk_bf16_f32 v72, v76, v77
	v_cvt_pk_bf16_f32 v73, v78, v79
	v_cvt_pk_bf16_f32 v74, v74, v75
	v_cvt_pk_bf16_f32 v75, v84, v85
	v_lshl_add_u64 v[76:77], v[154:155], 0, v[82:83]
	s_cbranch_vccnz .LBB0_1031
	s_mov_b64 s[34:35], 0
	global_store_dwordx4 v[76:77], v[72:75], off offset:512 sc0 sc1
.LBB0_1031:
	v_lshlrev_b64 v[78:79], 9, v[174:175]
	v_mov_b32_e32 v82, 0
	s_andn2_b64 vcc, exec, s[34:35]
	v_lshl_add_u64 v[78:79], v[150:151], 0, v[78:79]
	s_cbranch_vccnz .LBB0_1033
	global_store_dwordx4 v[78:79], v[72:75], off sc0 sc1
	v_lshlrev_b32_e32 v83, 16, v74
	v_and_b32_e32 v85, 0xffff0000, v74
	v_and_b32_e32 v84, 0xffff0000, v72
	v_lshlrev_b32_e32 v87, 16, v75
	v_and_b32_e32 v75, 0xffff0000, v75
	v_and_b32_e32 v74, 0xffff0000, v73
	v_lshlrev_b32_e32 v82, 16, v72
	v_lshlrev_b32_e32 v86, 16, v73
	v_pk_mul_f32 v[72:73], v[84:85], v[84:85]
	v_pk_mul_f32 v[74:75], v[74:75], v[74:75]
	v_pk_fma_f32 v[72:73], v[82:83], v[82:83], v[72:73]
	v_pk_fma_f32 v[74:75], v[86:87], v[86:87], v[74:75]
	s_nop 0
	v_pk_add_f32 v[72:73], v[72:73], v[74:75]
	s_nop 0
	v_add_f32_e32 v82, v72, v73

.LBB0_1036:
	global_store_dwordx4 v[76:77], v[64:67], off offset:768 sc0 sc1
	s_cbranch_execnz .LBB0_1035
.LBB0_1037:
	global_store_dwordx4 v[78:79], v[64:67], off offset:256 sc0 sc1
	v_lshlrev_b32_e32 v69, 16, v66
	v_and_b32_e32 v71, 0xffff0000, v66
	v_and_b32_e32 v70, 0xffff0000, v64
	v_lshlrev_b32_e32 v73, 16, v67
	v_and_b32_e32 v67, 0xffff0000, v67
	v_and_b32_e32 v66, 0xffff0000, v65
	v_lshlrev_b32_e32 v68, 16, v64
	v_lshlrev_b32_e32 v72, 16, v65
	v_pk_mul_f32 v[64:65], v[70:71], v[70:71]
	v_pk_mul_f32 v[66:67], v[66:67], v[66:67]
	v_pk_fma_f32 v[64:65], v[68:69], v[68:69], v[64:65]
	v_pk_fma_f32 v[66:67], v[72:73], v[72:73], v[66:67]
	s_nop 0
	v_pk_add_f32 v[64:65], v[64:65], v[66:67]
	s_nop 0
	v_add_f32_e32 v64, v64, v65
	v_add_f32_e32 v82, v64, v82
	s_and_b64 vcc, exec, s[42:43]
	s_cbranch_vccnz .LBB0_1041

.LBB0_1041:
	s_waitcnt lgkmcnt(0)
	v_pk_add_f32 v[64:65], v[136:137], v[138:139]
	v_lshlrev_b64 v[68:69], 10, v[172:173]
	v_pk_fma_f32 v[64:65], v[64:65], s[86:87], v[162:163] op_sel_hi:[1,0,0]
	s_mov_b64 s[34:35], -1
	v_mul_f32_e32 v66, 0x4b800000, v65
	v_cmp_gt_f32_e32 vcc, s26, v65
	v_cmp_gt_f32_e64 s[44:45], s26, v64
	s_nop 0
	v_cndmask_b32_e32 v65, v65, v66, vcc
	v_rsq_f32_e32 v65, v65
	s_nop 0
	v_mul_f32_e32 v66, 0x45800000, v65
	v_cndmask_b32_e32 v66, v65, v66, vcc
	v_pk_mul_f32 v[62:63], v[62:63], v[66:67] op_sel_hi:[1,0]
	v_pk_mul_f32 v[60:61], v[60:61], v[66:67] op_sel_hi:[1,0]
	v_pk_mul_f32 v[70:71], v[58:59], v[66:67] op_sel_hi:[1,0]
	v_pk_mul_f32 v[58:59], v[56:57], v[66:67] op_sel_hi:[1,0]
	v_cvt_pk_bf16_f32 v56, v60, v61
	v_cvt_pk_bf16_f32 v57, v62, v63
	v_cvt_pk_bf16_f32 v58, v58, v59
	v_cvt_pk_bf16_f32 v59, v70, v71
	s_and_b64 vcc, exec, s[4:5]
	v_lshl_add_u64 v[60:61], v[154:155], 0, v[68:69]
	s_cbranch_vccnz .LBB0_1043
	s_mov_b64 s[34:35], 0
	global_store_dwordx4 v[60:61], v[56:59], off offset:512 sc0 sc1
.LBB0_1043:
	v_lshlrev_b64 v[62:63], 9, v[172:173]
	v_mov_b32_e32 v65, 0
	s_andn2_b64 vcc, exec, s[34:35]
	v_lshl_add_u64 v[62:63], v[150:151], 0, v[62:63]
	s_cbranch_vccnz .LBB0_1045
	global_store_dwordx4 v[62:63], v[56:59], off sc0 sc1
	v_lshlrev_b32_e32 v69, 16, v58
	v_and_b32_e32 v71, 0xffff0000, v58
	v_and_b32_e32 v70, 0xffff0000, v56
	v_lshlrev_b32_e32 v73, 16, v59
	v_and_b32_e32 v59, 0xffff0000, v59
	v_and_b32_e32 v58, 0xffff0000, v57
	v_lshlrev_b32_e32 v68, 16, v56
	v_lshlrev_b32_e32 v72, 16, v57
	v_pk_mul_f32 v[56:57], v[70:71], v[70:71]
	v_pk_mul_f32 v[58:59], v[58:59], v[58:59]
	v_pk_fma_f32 v[56:57], v[68:69], v[68:69], v[56:57]
	v_pk_fma_f32 v[58:59], v[72:73], v[72:73], v[58:59]
	s_nop 0
	v_pk_add_f32 v[56:57], v[56:57], v[58:59]
	s_nop 0
	v_add_f32_e32 v65, v56, v57

.LBB0_1048:
	global_store_dwordx4 v[60:61], v[48:51], off offset:768 sc0 sc1
	s_cbranch_execnz .LBB0_1047
.LBB0_1049:
	global_store_dwordx4 v[62:63], v[48:51], off offset:256 sc0 sc1
	v_lshlrev_b32_e32 v53, 16, v50
	v_and_b32_e32 v55, 0xffff0000, v50
	v_and_b32_e32 v54, 0xffff0000, v48
	v_lshlrev_b32_e32 v57, 16, v51
	v_and_b32_e32 v51, 0xffff0000, v51
	v_and_b32_e32 v50, 0xffff0000, v49
	v_lshlrev_b32_e32 v52, 16, v48
	v_lshlrev_b32_e32 v56, 16, v49
	v_pk_mul_f32 v[48:49], v[54:55], v[54:55]
	v_pk_mul_f32 v[50:51], v[50:51], v[50:51]
	v_pk_fma_f32 v[48:49], v[52:53], v[52:53], v[48:49]
	v_pk_fma_f32 v[50:51], v[56:57], v[56:57], v[50:51]
	s_nop 0
	v_pk_add_f32 v[48:49], v[48:49], v[50:51]
	s_nop 0
	v_add_f32_e32 v48, v48, v49
	v_add_f32_e32 v65, v48, v65
	s_and_b64 vcc, exec, s[42:43]
	s_cbranch_vccnz .LBB0_1053

.LBB0_1053:
	v_mul_f32_e32 v48, 0x4b800000, v64
	v_cndmask_b32_e64 v48, v64, v48, s[44:45]
	v_rsq_f32_e32 v48, v48
	v_lshlrev_b64 v[50:51], 10, v[170:171]
	s_mov_b64 s[34:35], -1
	s_and_b64 vcc, exec, s[4:5]
	s_waitcnt lgkmcnt(0)
	v_mul_f32_e32 v49, 0x45800000, v48
	v_cndmask_b32_e64 v48, v48, v49, s[44:45]
	v_pk_mul_f32 v[46:47], v[46:47], v[48:49] op_sel_hi:[1,0]
	v_pk_mul_f32 v[44:45], v[44:45], v[48:49] op_sel_hi:[1,0]
	v_pk_mul_f32 v[52:53], v[42:43], v[48:49] op_sel_hi:[1,0]
	v_pk_mul_f32 v[42:43], v[40:41], v[48:49] op_sel_hi:[1,0]
	v_cvt_pk_bf16_f32 v40, v44, v45
	v_cvt_pk_bf16_f32 v41, v46, v47
	v_cvt_pk_bf16_f32 v42, v42, v43
	v_cvt_pk_bf16_f32 v43, v52, v53
	v_lshl_add_u64 v[44:45], v[154:155], 0, v[50:51]
	s_cbranch_vccnz .LBB0_1055
	s_mov_b64 s[34:35], 0
	global_store_dwordx4 v[44:45], v[40:43], off offset:512 sc0 sc1
.LBB0_1055:
	v_lshlrev_b64 v[46:47], 9, v[170:171]
	v_mov_b32_e32 v50, 0
	s_andn2_b64 vcc, exec, s[34:35]
	v_lshl_add_u64 v[46:47], v[150:151], 0, v[46:47]
	s_cbranch_vccnz .LBB0_1057
	global_store_dwordx4 v[46:47], v[40:43], off sc0 sc1
	v_lshlrev_b32_e32 v51, 16, v42
	v_and_b32_e32 v53, 0xffff0000, v42
	v_and_b32_e32 v52, 0xffff0000, v40
	v_lshlrev_b32_e32 v55, 16, v43
	v_and_b32_e32 v43, 0xffff0000, v43
	v_and_b32_e32 v42, 0xffff0000, v41
	v_lshlrev_b32_e32 v50, 16, v40
	v_lshlrev_b32_e32 v54, 16, v41
	v_pk_mul_f32 v[40:41], v[52:53], v[52:53]
	v_pk_mul_f32 v[42:43], v[42:43], v[42:43]
	v_pk_fma_f32 v[40:41], v[50:51], v[50:51], v[40:41]
	v_pk_fma_f32 v[42:43], v[54:55], v[54:55], v[42:43]
	s_nop 0
	v_pk_add_f32 v[40:41], v[40:41], v[42:43]
	s_nop 0
	v_add_f32_e32 v50, v40, v41

.LBB0_1060:
	global_store_dwordx4 v[44:45], v[32:35], off offset:768 sc0 sc1
	s_cbranch_execnz .LBB0_1059
.LBB0_1061:
	global_store_dwordx4 v[46:47], v[32:35], off offset:256 sc0 sc1
	v_lshlrev_b32_e32 v37, 16, v34
	v_and_b32_e32 v39, 0xffff0000, v34
	v_and_b32_e32 v38, 0xffff0000, v32
	v_lshlrev_b32_e32 v41, 16, v35
	v_and_b32_e32 v35, 0xffff0000, v35
	v_and_b32_e32 v34, 0xffff0000, v33
	v_lshlrev_b32_e32 v36, 16, v32
	v_lshlrev_b32_e32 v40, 16, v33
	v_pk_mul_f32 v[32:33], v[38:39], v[38:39]
	v_pk_mul_f32 v[34:35], v[34:35], v[34:35]
	v_pk_fma_f32 v[32:33], v[36:37], v[36:37], v[32:33]
	v_pk_fma_f32 v[34:35], v[40:41], v[40:41], v[34:35]
	s_nop 0
	v_pk_add_f32 v[32:33], v[32:33], v[34:35]
	s_nop 0
	v_add_f32_e32 v32, v32, v33
	v_add_f32_e32 v50, v32, v50
	s_and_b64 vcc, exec, s[42:43]
	s_cbranch_vccnz .LBB0_1065

.LBB0_1065:
	s_waitcnt lgkmcnt(0)
	v_pk_add_f32 v[32:33], v[128:129], v[130:131]
	v_lshlrev_b64 v[36:37], 10, v[168:169]
	v_pk_fma_f32 v[32:33], v[32:33], s[86:87], v[162:163] op_sel_hi:[1,0,0]
	s_mov_b64 s[34:35], -1
	v_mul_f32_e32 v34, 0x4b800000, v33
	v_cmp_gt_f32_e32 vcc, s26, v33
	v_cmp_gt_f32_e64 s[44:45], s26, v32
	s_nop 0
	v_cndmask_b32_e32 v33, v33, v34, vcc
	v_rsq_f32_e32 v33, v33
	s_nop 0
	v_mul_f32_e32 v34, 0x45800000, v33
	v_cndmask_b32_e32 v34, v33, v34, vcc
	v_pk_mul_f32 v[30:31], v[30:31], v[34:35] op_sel_hi:[1,0]
	v_pk_mul_f32 v[28:29], v[28:29], v[34:35] op_sel_hi:[1,0]
	v_pk_mul_f32 v[38:39], v[26:27], v[34:35] op_sel_hi:[1,0]
	v_pk_mul_f32 v[26:27], v[24:25], v[34:35] op_sel_hi:[1,0]
	v_cvt_pk_bf16_f32 v24, v28, v29
	v_cvt_pk_bf16_f32 v25, v30, v31
	v_cvt_pk_bf16_f32 v26, v26, v27
	v_cvt_pk_bf16_f32 v27, v38, v39
	s_and_b64 vcc, exec, s[4:5]
	v_lshl_add_u64 v[28:29], v[154:155], 0, v[36:37]
	s_cbranch_vccnz .LBB0_1067
	s_mov_b64 s[34:35], 0
	global_store_dwordx4 v[28:29], v[24:27], off offset:512 sc0 sc1
.LBB0_1067:
	v_lshlrev_b64 v[30:31], 9, v[168:169]
	v_mov_b32_e32 v33, 0
	s_andn2_b64 vcc, exec, s[34:35]
	v_lshl_add_u64 v[30:31], v[150:151], 0, v[30:31]
	s_cbranch_vccnz .LBB0_1069
	global_store_dwordx4 v[30:31], v[24:27], off sc0 sc1
	v_lshlrev_b32_e32 v37, 16, v26
	v_and_b32_e32 v39, 0xffff0000, v26
	v_and_b32_e32 v38, 0xffff0000, v24
	v_lshlrev_b32_e32 v41, 16, v27
	v_and_b32_e32 v27, 0xffff0000, v27
	v_and_b32_e32 v26, 0xffff0000, v25
	v_lshlrev_b32_e32 v36, 16, v24
	v_lshlrev_b32_e32 v40, 16, v25
	v_pk_mul_f32 v[24:25], v[38:39], v[38:39]
	v_pk_mul_f32 v[26:27], v[26:27], v[26:27]
	v_pk_fma_f32 v[24:25], v[36:37], v[36:37], v[24:25]
	v_pk_fma_f32 v[26:27], v[40:41], v[40:41], v[26:27]
	s_nop 0
	v_pk_add_f32 v[24:25], v[24:25], v[26:27]
	s_nop 0
	v_add_f32_e32 v33, v24, v25

.LBB0_1072:
	global_store_dwordx4 v[28:29], v[16:19], off offset:768 sc0 sc1
	s_cbranch_execnz .LBB0_1071
.LBB0_1073:
	global_store_dwordx4 v[30:31], v[16:19], off offset:256 sc0 sc1
	v_lshlrev_b32_e32 v21, 16, v18
	v_and_b32_e32 v23, 0xffff0000, v18
	v_and_b32_e32 v22, 0xffff0000, v16
	v_lshlrev_b32_e32 v25, 16, v19
	v_and_b32_e32 v19, 0xffff0000, v19
	v_and_b32_e32 v18, 0xffff0000, v17
	v_lshlrev_b32_e32 v20, 16, v16
	v_lshlrev_b32_e32 v24, 16, v17
	v_pk_mul_f32 v[16:17], v[22:23], v[22:23]
	v_pk_mul_f32 v[18:19], v[18:19], v[18:19]
	v_pk_fma_f32 v[16:17], v[20:21], v[20:21], v[16:17]
	v_pk_fma_f32 v[18:19], v[24:25], v[24:25], v[18:19]
	s_nop 0
	v_pk_add_f32 v[16:17], v[16:17], v[18:19]
	s_nop 0
	v_add_f32_e32 v16, v16, v17
	v_add_f32_e32 v33, v16, v33
	s_and_b64 vcc, exec, s[42:43]
	s_cbranch_vccnz .LBB0_1077

.LBB0_1077:
	v_mul_f32_e32 v16, 0x4b800000, v32
	v_cndmask_b32_e64 v16, v32, v16, s[44:45]
	v_rsq_f32_e32 v16, v16
	v_lshlrev_b64 v[18:19], 10, v[166:167]
	s_mov_b64 s[34:35], -1
	s_and_b64 vcc, exec, s[4:5]
	s_waitcnt lgkmcnt(0)
	v_mul_f32_e32 v17, 0x45800000, v16
	v_cndmask_b32_e64 v16, v16, v17, s[44:45]
	v_pk_mul_f32 v[14:15], v[14:15], v[16:17] op_sel_hi:[1,0]
	v_pk_mul_f32 v[12:13], v[12:13], v[16:17] op_sel_hi:[1,0]
	v_pk_mul_f32 v[20:21], v[10:11], v[16:17] op_sel_hi:[1,0]
	v_pk_mul_f32 v[10:11], v[8:9], v[16:17] op_sel_hi:[1,0]
	v_cvt_pk_bf16_f32 v8, v12, v13
	v_cvt_pk_bf16_f32 v9, v14, v15
	v_cvt_pk_bf16_f32 v10, v10, v11
	v_cvt_pk_bf16_f32 v11, v20, v21
	v_lshl_add_u64 v[12:13], v[154:155], 0, v[18:19]
	s_cbranch_vccnz .LBB0_1079
	s_mov_b64 s[34:35], 0
	global_store_dwordx4 v[12:13], v[8:11], off offset:512 sc0 sc1
.LBB0_1079:
	v_lshlrev_b64 v[14:15], 9, v[166:167]
	v_mov_b32_e32 v18, 0
	s_andn2_b64 vcc, exec, s[34:35]
	v_lshl_add_u64 v[14:15], v[150:151], 0, v[14:15]
	s_cbranch_vccnz .LBB0_1081
	global_store_dwordx4 v[14:15], v[8:11], off sc0 sc1
	v_lshlrev_b32_e32 v19, 16, v10
	v_and_b32_e32 v21, 0xffff0000, v10
	v_and_b32_e32 v20, 0xffff0000, v8
	v_lshlrev_b32_e32 v23, 16, v11
	v_and_b32_e32 v11, 0xffff0000, v11
	v_and_b32_e32 v10, 0xffff0000, v9
	v_lshlrev_b32_e32 v18, 16, v8
	v_lshlrev_b32_e32 v22, 16, v9
	v_pk_mul_f32 v[8:9], v[20:21], v[20:21]
	v_pk_mul_f32 v[10:11], v[10:11], v[10:11]
	v_pk_fma_f32 v[8:9], v[18:19], v[18:19], v[8:9]
	v_pk_fma_f32 v[10:11], v[22:23], v[22:23], v[10:11]
	s_nop 0
	v_pk_add_f32 v[8:9], v[8:9], v[10:11]
	s_nop 0
	v_add_f32_e32 v18, v8, v9

.LBB0_1085:
	global_store_dwordx4 v[12:13], v[0:3], off offset:768 sc0 sc1
	s_cbranch_execnz .LBB0_1083
.LBB0_1086:
	global_store_dwordx4 v[14:15], v[0:3], off offset:256 sc0 sc1
	v_lshlrev_b32_e32 v5, 16, v2
	v_and_b32_e32 v7, 0xffff0000, v2
	v_and_b32_e32 v6, 0xffff0000, v0
	v_lshlrev_b32_e32 v9, 16, v3
	v_and_b32_e32 v3, 0xffff0000, v3
	v_and_b32_e32 v2, 0xffff0000, v1
	v_lshlrev_b32_e32 v4, 16, v0
	v_lshlrev_b32_e32 v8, 16, v1
	v_pk_mul_f32 v[0:1], v[6:7], v[6:7]
	v_pk_mul_f32 v[2:3], v[2:3], v[2:3]
	v_pk_fma_f32 v[0:1], v[4:5], v[4:5], v[0:1]
	v_pk_fma_f32 v[2:3], v[8:9], v[8:9], v[2:3]
	s_nop 0
	v_pk_add_f32 v[0:1], v[0:1], v[2:3]
	s_nop 0
	v_add_f32_e32 v0, v0, v1
	v_add_f32_e32 v18, v0, v18
	s_and_b64 vcc, exec, s[42:43]
	s_cbranch_vccnz .LBB0_1084

.LBB0_1310:
	s_lshl_b32 s10, s42, 2
	s_add_i32 s66, s10, s78
	s_cmp_gt_i32 s66, 5
	s_cbranch_scc1 .LBB0_1312
	v_ashrrev_i32_e32 v153, 31, v152
	v_lshl_add_u64 v[128:129], v[152:153], 4, s[20:21]
	global_load_dwordx4 v[128:131], v[128:129], off
	s_waitcnt vmcnt(0)
	v_mov_b32_e32 v132, v129
	v_mov_b32_e32 v133, v130
	v_mov_b32_e32 v129, v131
	v_pk_add_f32 v[128:129], v[132:133], v[128:129]
	s_nop 0
	v_add_f32_e32 v128, v128, v129
	v_fmamk_f32 v128, v128, 0x3b800000, v162
	v_cmp_gt_f32_e32 vcc, s26, v128
	v_mul_f32_e32 v129, 0x4b800000, v128
	s_nop 0
	v_cndmask_b32_e32 v128, v128, v129, vcc
	v_rsq_f32_e32 v128, v128
	s_nop 0
	v_mul_f32_e32 v129, 0x45800000, v128
	v_cndmask_b32_e32 v128, v128, v129, vcc
	v_mul_f32_e32 v154, 0x3dd53b94, v128
	v_lshlrev_b64 v[128:129], 8, v[152:153]
	v_lshl_add_u64 v[170:171], v[142:143], 0, v[128:129]
	global_load_dwordx4 v[128:131], v[170:171], off offset:48
	global_load_dwordx4 v[132:135], v[170:171], off offset:32
	global_load_dwordx4 v[166:169], v[170:171], off offset:16
	s_nop 0
	global_load_dwordx4 v[170:173], v[170:171], off
	s_waitcnt vmcnt(0)
	v_mov_b32_e32 v174, v171
	v_mov_b32_e32 v175, v173
	v_pk_mul_f32 v[176:177], v[120:121], v[174:175]
	v_mov_b32_e32 v171, v172
	v_pk_mul_f32 v[174:175], v[116:117], v[174:175]
	v_pk_fma_f32 v[172:173], v[116:117], v[170:171], v[176:177]
	v_pk_fma_f32 v[170:171], v[120:121], v[170:171], v[174:175] neg_lo:[0,0,1] neg_hi:[0,0,1]
	v_mov_b32_e32 v174, v167
	v_mov_b32_e32 v175, v169
	v_pk_mul_f32 v[176:177], v[122:123], v[174:175]
	v_mov_b32_e32 v167, v168
	v_pk_mul_f32 v[174:175], v[118:119], v[174:175]
	v_pk_fma_f32 v[168:169], v[118:119], v[166:167], v[176:177]
	v_pk_fma_f32 v[166:167], v[122:123], v[166:167], v[174:175] neg_lo:[0,0,1] neg_hi:[0,0,1]
	v_mov_b32_e32 v174, v133
	v_mov_b32_e32 v175, v135
	v_pk_mul_f32 v[176:177], v[124:125], v[174:175]
	v_mov_b32_e32 v133, v134
	v_pk_mul_f32 v[174:175], v[112:113], v[174:175]
	v_pk_fma_f32 v[134:135], v[112:113], v[132:133], v[176:177]
	v_pk_fma_f32 v[132:133], v[124:125], v[132:133], v[174:175] neg_lo:[0,0,1] neg_hi:[0,0,1]
	v_mov_b32_e32 v174, v129
	v_mov_b32_e32 v175, v131
	v_pk_mul_f32 v[176:177], v[126:127], v[174:175]
	v_mov_b32_e32 v129, v130
	v_pk_fma_f32 v[130:131], v[114:115], v[128:129], v[176:177]
	v_pk_mul_f32 v[172:173], v[172:173], v[154:155] op_sel_hi:[1,0]
	v_pk_mul_f32 v[176:177], v[154:155], v[130:131] op_sel_hi:[0,1]
	v_pk_mul_f32 v[130:131], v[114:115], v[174:175]
	v_pk_mul_f32 v[170:171], v[170:171], v[154:155] op_sel_hi:[1,0]
	v_pk_fma_f32 v[128:129], v[126:127], v[128:129], v[130:131] neg_lo:[0,0,1] neg_hi:[0,0,1]
	v_pk_mul_f32 v[168:169], v[168:169], v[154:155] op_sel_hi:[1,0]
	v_pk_mul_f32 v[166:167], v[166:167], v[154:155] op_sel_hi:[1,0]
	v_pk_mul_f32 v[134:135], v[154:155], v[134:135] op_sel_hi:[0,1]
	v_pk_mul_f32 v[132:133], v[154:155], v[132:133] op_sel_hi:[0,1]
	v_pk_mul_f32 v[154:155], v[154:155], v[128:129] op_sel_hi:[0,1]
	v_cvt_pk_bf16_f32 v131, v154, v155
	v_mad_i64_i32 v[154:155], s[30:31], v152, 6, s[66:67]
	v_cvt_pk_bf16_f32 v129, v166, v167
	v_mad_u64_u32 v[166:167], s[30:31], v154, s6, v[146:147]
	v_cvt_pk_bf16_f32 v128, v170, v171
	v_cvt_pk_bf16_f32 v130, v132, v133
	v_mad_i32_i24 v167, v155, s6, v167
	v_cvt_pk_bf16_f32 v132, v172, v173
	v_cvt_pk_bf16_f32 v133, v168, v169
	v_cvt_pk_bf16_f32 v134, v134, v135
	v_cvt_pk_bf16_f32 v135, v176, v177
	global_store_dwordx4 v[166:167], v[128:131], off offset:256 sc0 sc1
	global_store_dwordx4 v[166:167], v[132:135], off offset:320 sc0 sc1
	s_nop 0
	v_or_b32_e32 v128, 16, v152
	v_ashrrev_i32_e32 v129, 31, v128
	v_lshl_add_u64 v[130:131], v[128:129], 4, s[20:21]
	global_load_dwordx4 v[130:133], v[130:131], off
	s_waitcnt vmcnt(0)
	v_mov_b32_e32 v134, v131
	v_mov_b32_e32 v135, v132
	v_mov_b32_e32 v131, v133
	v_pk_add_f32 v[130:131], v[134:135], v[130:131]
	s_nop 0
	v_add_f32_e32 v130, v130, v131
	v_fmamk_f32 v130, v130, 0x3b800000, v162
	v_cmp_gt_f32_e32 vcc, s26, v130
	v_mul_f32_e32 v131, 0x4b800000, v130
	s_nop 0
	v_cndmask_b32_e32 v130, v130, v131, vcc
	v_rsq_f32_e32 v130, v130
	s_nop 0
	v_mul_f32_e32 v131, 0x45800000, v130
	v_cndmask_b32_e32 v130, v130, v131, vcc
	v_mul_f32_e32 v134, 0x3dd53b94, v130
	v_lshlrev_b64 v[130:131], 8, v[128:129]
	v_lshl_add_u64 v[154:155], v[142:143], 0, v[130:131]
	global_load_dwordx4 v[130:133], v[154:155], off offset:48
	global_load_dwordx4 v[166:169], v[154:155], off offset:32
	global_load_dwordx4 v[170:173], v[154:155], off offset:16
	global_load_dwordx4 v[174:177], v[154:155], off
	v_mad_i64_i32 v[128:129], s[30:31], v128, 6, s[66:67]
	s_waitcnt vmcnt(0)
	v_mov_b32_e32 v154, v175
	v_mov_b32_e32 v155, v177
	v_pk_mul_f32 v[178:179], v[108:109], v[154:155]
	v_mov_b32_e32 v175, v176
	v_pk_mul_f32 v[154:155], v[100:101], v[154:155]
	v_pk_fma_f32 v[176:177], v[100:101], v[174:175], v[178:179]
	v_pk_fma_f32 v[154:155], v[108:109], v[174:175], v[154:155] neg_lo:[0,0,1] neg_hi:[0,0,1]
	v_mov_b32_e32 v174, v171
	v_mov_b32_e32 v175, v173
	v_pk_mul_f32 v[178:179], v[110:111], v[174:175]
	v_mov_b32_e32 v171, v172
	v_pk_mul_f32 v[174:175], v[102:103], v[174:175]
	v_pk_fma_f32 v[172:173], v[102:103], v[170:171], v[178:179]
	v_pk_fma_f32 v[170:171], v[110:111], v[170:171], v[174:175] neg_lo:[0,0,1] neg_hi:[0,0,1]
	v_mov_b32_e32 v174, v167
	v_mov_b32_e32 v175, v169
	v_pk_mul_f32 v[178:179], v[104:105], v[174:175]
	v_mov_b32_e32 v167, v168
	v_pk_mul_f32 v[174:175], v[96:97], v[174:175]
	v_pk_fma_f32 v[168:169], v[96:97], v[166:167], v[178:179]
	v_pk_fma_f32 v[166:167], v[104:105], v[166:167], v[174:175] neg_lo:[0,0,1] neg_hi:[0,0,1]
	v_mov_b32_e32 v174, v131
	v_mov_b32_e32 v175, v133
	v_pk_mul_f32 v[178:179], v[106:107], v[174:175]
	v_mov_b32_e32 v131, v132
	v_pk_fma_f32 v[132:133], v[98:99], v[130:131], v[178:179]
	v_pk_mul_f32 v[176:177], v[176:177], v[134:135] op_sel_hi:[1,0]
	v_pk_mul_f32 v[178:179], v[134:135], v[132:133] op_sel_hi:[0,1]
	v_pk_mul_f32 v[132:133], v[98:99], v[174:175]
	v_pk_mul_f32 v[154:155], v[154:155], v[134:135] op_sel_hi:[1,0]
	v_pk_fma_f32 v[130:131], v[106:107], v[130:131], v[132:133] neg_lo:[0,0,1] neg_hi:[0,0,1]
	v_pk_mul_f32 v[172:173], v[172:173], v[134:135] op_sel_hi:[1,0]
	v_pk_mul_f32 v[170:171], v[170:171], v[134:135] op_sel_hi:[1,0]
	v_pk_mul_f32 v[168:169], v[134:135], v[168:169] op_sel_hi:[0,1]
	v_pk_mul_f32 v[166:167], v[134:135], v[166:167] op_sel_hi:[0,1]
	v_pk_mul_f32 v[134:135], v[134:135], v[130:131] op_sel_hi:[0,1]
	v_cvt_pk_bf16_f32 v133, v134, v135
	v_mad_u64_u32 v[134:135], s[30:31], v128, s6, v[146:147]
	v_or_b32_e32 v128, 32, v152
	v_cvt_pk_bf16_f32 v130, v154, v155
	v_cvt_pk_bf16_f32 v131, v170, v171
	v_cvt_pk_bf16_f32 v132, v166, v167
	v_mad_i32_i24 v135, v129, s6, v135
	v_ashrrev_i32_e32 v129, 31, v128
	v_cvt_pk_bf16_f32 v166, v176, v177
	v_cvt_pk_bf16_f32 v167, v172, v173
	v_cvt_pk_bf16_f32 v168, v168, v169
	v_cvt_pk_bf16_f32 v169, v178, v179
	global_store_dwordx4 v[134:135], v[130:133], off offset:256 sc0 sc1
	global_store_dwordx4 v[134:135], v[166:169], off offset:320 sc0 sc1
	s_nop 0
	v_lshl_add_u64 v[130:131], v[128:129], 4, s[20:21]
	global_load_dwordx4 v[130:133], v[130:131], off
	s_waitcnt vmcnt(0)
	v_mov_b32_e32 v134, v131
	v_mov_b32_e32 v135, v132
	v_mov_b32_e32 v131, v133
	v_pk_add_f32 v[130:131], v[134:135], v[130:131]
	s_nop 0
	v_add_f32_e32 v130, v130, v131
	v_fmamk_f32 v130, v130, 0x3b800000, v162
	v_cmp_gt_f32_e32 vcc, s26, v130
	v_mul_f32_e32 v131, 0x4b800000, v130
	s_nop 0
	v_cndmask_b32_e32 v130, v130, v131, vcc
	v_rsq_f32_e32 v130, v130
	s_nop 0
	v_mul_f32_e32 v131, 0x45800000, v130
	v_cndmask_b32_e32 v130, v130, v131, vcc
	v_mul_f32_e32 v134, 0x3dd53b94, v130
	v_lshlrev_b64 v[130:131], 8, v[128:129]
	v_lshl_add_u64 v[154:155], v[142:143], 0, v[130:131]
	global_load_dwordx4 v[130:133], v[154:155], off offset:48
	global_load_dwordx4 v[166:169], v[154:155], off offset:32
	global_load_dwordx4 v[170:173], v[154:155], off offset:16
	global_load_dwordx4 v[174:177], v[154:155], off
	v_mad_i64_i32 v[128:129], s[30:31], v128, 6, s[66:67]
	s_waitcnt vmcnt(0)
	v_mov_b32_e32 v154, v175
	v_mov_b32_e32 v155, v177
	v_pk_mul_f32 v[178:179], v[92:93], v[154:155]
	v_mov_b32_e32 v175, v176
	v_pk_mul_f32 v[154:155], v[84:85], v[154:155]
	v_pk_fma_f32 v[176:177], v[84:85], v[174:175], v[178:179]
	v_pk_fma_f32 v[154:155], v[92:93], v[174:175], v[154:155] neg_lo:[0,0,1] neg_hi:[0,0,1]
	v_mov_b32_e32 v174, v171
	v_mov_b32_e32 v175, v173
	v_pk_mul_f32 v[178:179], v[94:95], v[174:175]
	v_mov_b32_e32 v171, v172
	v_pk_mul_f32 v[174:175], v[86:87], v[174:175]
	v_pk_fma_f32 v[172:173], v[86:87], v[170:171], v[178:179]
	v_pk_fma_f32 v[170:171], v[94:95], v[170:171], v[174:175] neg_lo:[0,0,1] neg_hi:[0,0,1]
	v_mov_b32_e32 v174, v167
	v_mov_b32_e32 v175, v169
	v_pk_mul_f32 v[178:179], v[88:89], v[174:175]
	v_mov_b32_e32 v167, v168
	v_pk_mul_f32 v[174:175], v[80:81], v[174:175]
	v_pk_fma_f32 v[168:169], v[80:81], v[166:167], v[178:179]
	v_pk_fma_f32 v[166:167], v[88:89], v[166:167], v[174:175] neg_lo:[0,0,1] neg_hi:[0,0,1]
	v_mov_b32_e32 v174, v131
	v_mov_b32_e32 v175, v133
	v_pk_mul_f32 v[178:179], v[90:91], v[174:175]
	v_mov_b32_e32 v131, v132
	v_pk_fma_f32 v[132:133], v[82:83], v[130:131], v[178:179]
	v_pk_mul_f32 v[176:177], v[176:177], v[134:135] op_sel_hi:[1,0]
	v_pk_mul_f32 v[178:179], v[134:135], v[132:133] op_sel_hi:[0,1]
	v_pk_mul_f32 v[132:133], v[82:83], v[174:175]
	v_pk_mul_f32 v[154:155], v[154:155], v[134:135] op_sel_hi:[1,0]
	v_pk_fma_f32 v[130:131], v[90:91], v[130:131], v[132:133] neg_lo:[0,0,1] neg_hi:[0,0,1]
	v_pk_mul_f32 v[172:173], v[172:173], v[134:135] op_sel_hi:[1,0]
	v_pk_mul_f32 v[170:171], v[170:171], v[134:135] op_sel_hi:[1,0]
	v_pk_mul_f32 v[168:169], v[134:135], v[168:169] op_sel_hi:[0,1]
	v_pk_mul_f32 v[166:167], v[134:135], v[166:167] op_sel_hi:[0,1]
	v_pk_mul_f32 v[134:135], v[134:135], v[130:131] op_sel_hi:[0,1]
	v_cvt_pk_bf16_f32 v133, v134, v135
	v_mad_u64_u32 v[134:135], s[30:31], v128, s6, v[146:147]
	v_or_b32_e32 v128, 48, v152
	v_cvt_pk_bf16_f32 v130, v154, v155
	v_cvt_pk_bf16_f32 v131, v170, v171
	v_cvt_pk_bf16_f32 v132, v166, v167
	v_mad_i32_i24 v135, v129, s6, v135
	v_ashrrev_i32_e32 v129, 31, v128
	v_cvt_pk_bf16_f32 v166, v176, v177
	v_cvt_pk_bf16_f32 v167, v172, v173
	v_cvt_pk_bf16_f32 v168, v168, v169
	v_cvt_pk_bf16_f32 v169, v178, v179
	global_store_dwordx4 v[134:135], v[130:133], off offset:256 sc0 sc1
	global_store_dwordx4 v[134:135], v[166:169], off offset:320 sc0 sc1
	s_nop 0
	v_lshl_add_u64 v[130:131], v[128:129], 4, s[20:21]
	global_load_dwordx4 v[130:133], v[130:131], off
	s_waitcnt vmcnt(0)
	v_mov_b32_e32 v134, v131
	v_mov_b32_e32 v135, v132
	v_mov_b32_e32 v131, v133
	v_pk_add_f32 v[130:131], v[134:135], v[130:131]
	s_nop 0
	v_add_f32_e32 v130, v130, v131
	v_fmamk_f32 v130, v130, 0x3b800000, v162
	v_cmp_gt_f32_e32 vcc, s26, v130
	v_mul_f32_e32 v131, 0x4b800000, v130
	s_nop 0
	v_cndmask_b32_e32 v130, v130, v131, vcc
	v_rsq_f32_e32 v130, v130
	s_nop 0
	v_mul_f32_e32 v131, 0x45800000, v130
	v_cndmask_b32_e32 v130, v130, v131, vcc
	v_mul_f32_e32 v134, 0x3dd53b94, v130
	v_lshlrev_b64 v[130:131], 8, v[128:129]
	v_lshl_add_u64 v[154:155], v[142:143], 0, v[130:131]
	global_load_dwordx4 v[130:133], v[154:155], off offset:48
	global_load_dwordx4 v[166:169], v[154:155], off offset:32
	global_load_dwordx4 v[170:173], v[154:155], off offset:16
	global_load_dwordx4 v[174:177], v[154:155], off
	v_mad_i64_i32 v[128:129], s[30:31], v128, 6, s[66:67]
	s_waitcnt vmcnt(0)
	v_mov_b32_e32 v154, v175
	v_mov_b32_e32 v155, v177
	v_pk_mul_f32 v[178:179], v[76:77], v[154:155]
	v_mov_b32_e32 v175, v176
	v_pk_mul_f32 v[154:155], v[68:69], v[154:155]
	v_pk_fma_f32 v[176:177], v[68:69], v[174:175], v[178:179]
	v_pk_fma_f32 v[154:155], v[76:77], v[174:175], v[154:155] neg_lo:[0,0,1] neg_hi:[0,0,1]
	v_mov_b32_e32 v174, v171
	v_mov_b32_e32 v175, v173
	v_pk_mul_f32 v[178:179], v[78:79], v[174:175]
	v_mov_b32_e32 v171, v172
	v_pk_mul_f32 v[174:175], v[70:71], v[174:175]
	v_pk_fma_f32 v[172:173], v[70:71], v[170:171], v[178:179]
	v_pk_fma_f32 v[170:171], v[78:79], v[170:171], v[174:175] neg_lo:[0,0,1] neg_hi:[0,0,1]
	v_mov_b32_e32 v174, v167
	v_mov_b32_e32 v175, v169
	v_pk_mul_f32 v[178:179], v[72:73], v[174:175]
	v_mov_b32_e32 v167, v168
	v_pk_mul_f32 v[174:175], v[64:65], v[174:175]
	v_pk_fma_f32 v[168:169], v[64:65], v[166:167], v[178:179]
	v_pk_fma_f32 v[166:167], v[72:73], v[166:167], v[174:175] neg_lo:[0,0,1] neg_hi:[0,0,1]
	v_mov_b32_e32 v174, v131
	v_mov_b32_e32 v175, v133
	v_pk_mul_f32 v[178:179], v[74:75], v[174:175]
	v_mov_b32_e32 v131, v132
	v_pk_fma_f32 v[132:133], v[66:67], v[130:131], v[178:179]
	v_pk_mul_f32 v[176:177], v[176:177], v[134:135] op_sel_hi:[1,0]
	v_pk_mul_f32 v[178:179], v[134:135], v[132:133] op_sel_hi:[0,1]
	v_pk_mul_f32 v[132:133], v[66:67], v[174:175]
	v_pk_mul_f32 v[154:155], v[154:155], v[134:135] op_sel_hi:[1,0]
	v_pk_fma_f32 v[130:131], v[74:75], v[130:131], v[132:133] neg_lo:[0,0,1] neg_hi:[0,0,1]
	v_pk_mul_f32 v[172:173], v[172:173], v[134:135] op_sel_hi:[1,0]
	v_pk_mul_f32 v[170:171], v[170:171], v[134:135] op_sel_hi:[1,0]
	v_pk_mul_f32 v[168:169], v[134:135], v[168:169] op_sel_hi:[0,1]
	v_pk_mul_f32 v[166:167], v[134:135], v[166:167] op_sel_hi:[0,1]
	v_pk_mul_f32 v[134:135], v[134:135], v[130:131] op_sel_hi:[0,1]
	v_cvt_pk_bf16_f32 v133, v134, v135
	v_mad_u64_u32 v[134:135], s[30:31], v128, s6, v[146:147]
	v_add_u32_e32 v128, 0x80, v152
	v_cvt_pk_bf16_f32 v130, v154, v155
	v_cvt_pk_bf16_f32 v131, v170, v171
	v_cvt_pk_bf16_f32 v132, v166, v167
	v_mad_i32_i24 v135, v129, s6, v135
	v_ashrrev_i32_e32 v129, 31, v128
	v_cvt_pk_bf16_f32 v166, v176, v177
	v_cvt_pk_bf16_f32 v167, v172, v173
	v_cvt_pk_bf16_f32 v168, v168, v169
	v_cvt_pk_bf16_f32 v169, v178, v179
	global_store_dwordx4 v[134:135], v[130:133], off offset:256 sc0 sc1
	global_store_dwordx4 v[134:135], v[166:169], off offset:320 sc0 sc1
	s_nop 0
	v_lshl_add_u64 v[130:131], v[128:129], 4, s[20:21]
	global_load_dwordx4 v[130:133], v[130:131], off
	s_waitcnt vmcnt(0)
	v_mov_b32_e32 v134, v131
	v_mov_b32_e32 v135, v132
	v_mov_b32_e32 v131, v133
	v_pk_add_f32 v[130:131], v[134:135], v[130:131]
	s_nop 0
	v_add_f32_e32 v130, v130, v131
	v_fmamk_f32 v130, v130, 0x3b800000, v162
	v_cmp_gt_f32_e32 vcc, s26, v130
	v_mul_f32_e32 v131, 0x4b800000, v130
	s_nop 0
	v_cndmask_b32_e32 v130, v130, v131, vcc
	v_rsq_f32_e32 v130, v130
	s_nop 0
	v_mul_f32_e32 v131, 0x45800000, v130
	v_cndmask_b32_e32 v130, v130, v131, vcc
	v_mul_f32_e32 v134, 0x3dd53b94, v130
	v_lshlrev_b64 v[130:131], 8, v[128:129]
	v_lshl_add_u64 v[154:155], v[142:143], 0, v[130:131]
	global_load_dwordx4 v[130:133], v[154:155], off offset:48
	global_load_dwordx4 v[166:169], v[154:155], off offset:32
	global_load_dwordx4 v[170:173], v[154:155], off offset:16
	global_load_dwordx4 v[174:177], v[154:155], off
	v_mad_i64_i32 v[128:129], s[30:31], v128, 6, s[66:67]
	s_waitcnt vmcnt(0)
	v_mov_b32_e32 v154, v175
	v_mov_b32_e32 v155, v177
	v_pk_mul_f32 v[178:179], v[60:61], v[154:155]
	v_mov_b32_e32 v175, v176
	v_pk_mul_f32 v[154:155], v[52:53], v[154:155]
	v_pk_fma_f32 v[176:177], v[52:53], v[174:175], v[178:179]
	v_pk_fma_f32 v[154:155], v[60:61], v[174:175], v[154:155] neg_lo:[0,0,1] neg_hi:[0,0,1]
	v_mov_b32_e32 v174, v171
	v_mov_b32_e32 v175, v173
	v_pk_mul_f32 v[178:179], v[62:63], v[174:175]
	v_mov_b32_e32 v171, v172
	v_pk_mul_f32 v[174:175], v[54:55], v[174:175]
	v_pk_fma_f32 v[172:173], v[54:55], v[170:171], v[178:179]
	v_pk_fma_f32 v[170:171], v[62:63], v[170:171], v[174:175] neg_lo:[0,0,1] neg_hi:[0,0,1]
	v_mov_b32_e32 v174, v167
	v_mov_b32_e32 v175, v169
	v_pk_mul_f32 v[178:179], v[56:57], v[174:175]
	v_mov_b32_e32 v167, v168
	v_pk_mul_f32 v[174:175], v[48:49], v[174:175]
	v_pk_fma_f32 v[168:169], v[48:49], v[166:167], v[178:179]
	v_pk_fma_f32 v[166:167], v[56:57], v[166:167], v[174:175] neg_lo:[0,0,1] neg_hi:[0,0,1]
	v_mov_b32_e32 v174, v131
	v_mov_b32_e32 v175, v133
	v_pk_mul_f32 v[178:179], v[58:59], v[174:175]
	v_mov_b32_e32 v131, v132
	v_pk_fma_f32 v[132:133], v[50:51], v[130:131], v[178:179]
	v_pk_mul_f32 v[176:177], v[176:177], v[134:135] op_sel_hi:[1,0]
	v_pk_mul_f32 v[178:179], v[134:135], v[132:133] op_sel_hi:[0,1]
	v_pk_mul_f32 v[132:133], v[50:51], v[174:175]
	v_pk_mul_f32 v[154:155], v[154:155], v[134:135] op_sel_hi:[1,0]
	v_pk_fma_f32 v[130:131], v[58:59], v[130:131], v[132:133] neg_lo:[0,0,1] neg_hi:[0,0,1]
	v_pk_mul_f32 v[172:173], v[172:173], v[134:135] op_sel_hi:[1,0]
	v_pk_mul_f32 v[170:171], v[170:171], v[134:135] op_sel_hi:[1,0]
	v_pk_mul_f32 v[168:169], v[134:135], v[168:169] op_sel_hi:[0,1]
	v_pk_mul_f32 v[166:167], v[134:135], v[166:167] op_sel_hi:[0,1]
	v_pk_mul_f32 v[134:135], v[134:135], v[130:131] op_sel_hi:[0,1]
	v_cvt_pk_bf16_f32 v133, v134, v135
	v_mad_u64_u32 v[134:135], s[30:31], v128, s6, v[146:147]
	v_add_u32_e32 v128, 0x90, v152
	v_cvt_pk_bf16_f32 v130, v154, v155
	v_cvt_pk_bf16_f32 v131, v170, v171
	v_cvt_pk_bf16_f32 v132, v166, v167
	v_mad_i32_i24 v135, v129, s6, v135
	v_ashrrev_i32_e32 v129, 31, v128
	v_cvt_pk_bf16_f32 v166, v176, v177
	v_cvt_pk_bf16_f32 v167, v172, v173
	v_cvt_pk_bf16_f32 v168, v168, v169
	v_cvt_pk_bf16_f32 v169, v178, v179
	global_store_dwordx4 v[134:135], v[130:133], off offset:256 sc0 sc1
	global_store_dwordx4 v[134:135], v[166:169], off offset:320 sc0 sc1
	s_nop 0
	v_lshl_add_u64 v[130:131], v[128:129], 4, s[20:21]
	global_load_dwordx4 v[130:133], v[130:131], off
	s_waitcnt vmcnt(0)
	v_mov_b32_e32 v134, v131
	v_mov_b32_e32 v135, v132
	v_mov_b32_e32 v131, v133
	v_pk_add_f32 v[130:131], v[134:135], v[130:131]
	s_nop 0
	v_add_f32_e32 v130, v130, v131
	v_fmamk_f32 v130, v130, 0x3b800000, v162
	v_cmp_gt_f32_e32 vcc, s26, v130
	v_mul_f32_e32 v131, 0x4b800000, v130
	s_nop 0
	v_cndmask_b32_e32 v130, v130, v131, vcc
	v_rsq_f32_e32 v130, v130
	s_nop 0
	v_mul_f32_e32 v131, 0x45800000, v130
	v_cndmask_b32_e32 v130, v130, v131, vcc
	v_mul_f32_e32 v134, 0x3dd53b94, v130
	v_lshlrev_b64 v[130:131], 8, v[128:129]
	v_lshl_add_u64 v[154:155], v[142:143], 0, v[130:131]
	global_load_dwordx4 v[130:133], v[154:155], off offset:48
	global_load_dwordx4 v[166:169], v[154:155], off offset:32
	global_load_dwordx4 v[170:173], v[154:155], off offset:16
	global_load_dwordx4 v[174:177], v[154:155], off
	v_mad_i64_i32 v[128:129], s[30:31], v128, 6, s[66:67]
	s_waitcnt vmcnt(0)
	v_mov_b32_e32 v154, v175
	v_mov_b32_e32 v155, v177
	v_pk_mul_f32 v[178:179], v[44:45], v[154:155]
	v_mov_b32_e32 v175, v176
	v_pk_mul_f32 v[154:155], v[36:37], v[154:155]
	v_pk_fma_f32 v[176:177], v[36:37], v[174:175], v[178:179]
	v_pk_fma_f32 v[154:155], v[44:45], v[174:175], v[154:155] neg_lo:[0,0,1] neg_hi:[0,0,1]
	v_mov_b32_e32 v174, v171
	v_mov_b32_e32 v175, v173
	v_pk_mul_f32 v[178:179], v[46:47], v[174:175]
	v_mov_b32_e32 v171, v172
	v_pk_mul_f32 v[174:175], v[38:39], v[174:175]
	v_pk_fma_f32 v[172:173], v[38:39], v[170:171], v[178:179]
	v_pk_fma_f32 v[170:171], v[46:47], v[170:171], v[174:175] neg_lo:[0,0,1] neg_hi:[0,0,1]
	v_mov_b32_e32 v174, v167
	v_mov_b32_e32 v175, v169
	v_pk_mul_f32 v[178:179], v[40:41], v[174:175]
	v_mov_b32_e32 v167, v168
	v_pk_mul_f32 v[174:175], v[32:33], v[174:175]
	v_pk_fma_f32 v[168:169], v[32:33], v[166:167], v[178:179]
	v_pk_fma_f32 v[166:167], v[40:41], v[166:167], v[174:175] neg_lo:[0,0,1] neg_hi:[0,0,1]
	v_mov_b32_e32 v174, v131
	v_mov_b32_e32 v175, v133
	v_pk_mul_f32 v[178:179], v[42:43], v[174:175]
	v_mov_b32_e32 v131, v132
	v_pk_fma_f32 v[132:133], v[34:35], v[130:131], v[178:179]
	v_pk_mul_f32 v[176:177], v[176:177], v[134:135] op_sel_hi:[1,0]
	v_pk_mul_f32 v[178:179], v[134:135], v[132:133] op_sel_hi:[0,1]
	v_pk_mul_f32 v[132:133], v[34:35], v[174:175]
	v_pk_mul_f32 v[154:155], v[154:155], v[134:135] op_sel_hi:[1,0]
	v_pk_fma_f32 v[130:131], v[42:43], v[130:131], v[132:133] neg_lo:[0,0,1] neg_hi:[0,0,1]
	v_pk_mul_f32 v[172:173], v[172:173], v[134:135] op_sel_hi:[1,0]
	v_pk_mul_f32 v[170:171], v[170:171], v[134:135] op_sel_hi:[1,0]
	v_pk_mul_f32 v[168:169], v[134:135], v[168:169] op_sel_hi:[0,1]
	v_pk_mul_f32 v[166:167], v[134:135], v[166:167] op_sel_hi:[0,1]
	v_pk_mul_f32 v[134:135], v[134:135], v[130:131] op_sel_hi:[0,1]
	v_cvt_pk_bf16_f32 v133, v134, v135
	v_mad_u64_u32 v[134:135], s[30:31], v128, s6, v[146:147]
	v_add_u32_e32 v128, 0xa0, v152
	v_cvt_pk_bf16_f32 v130, v154, v155
	v_cvt_pk_bf16_f32 v131, v170, v171
	v_cvt_pk_bf16_f32 v132, v166, v167
	v_mad_i32_i24 v135, v129, s6, v135
	v_ashrrev_i32_e32 v129, 31, v128
	v_cvt_pk_bf16_f32 v166, v176, v177
	v_cvt_pk_bf16_f32 v167, v172, v173
	v_cvt_pk_bf16_f32 v168, v168, v169
	v_cvt_pk_bf16_f32 v169, v178, v179
	global_store_dwordx4 v[134:135], v[130:133], off offset:256 sc0 sc1
	global_store_dwordx4 v[134:135], v[166:169], off offset:320 sc0 sc1
	s_nop 0
	v_lshl_add_u64 v[130:131], v[128:129], 4, s[20:21]
	global_load_dwordx4 v[130:133], v[130:131], off
	s_waitcnt vmcnt(0)
	v_mov_b32_e32 v134, v131
	v_mov_b32_e32 v135, v132
	v_mov_b32_e32 v131, v133
	v_pk_add_f32 v[130:131], v[134:135], v[130:131]
	s_nop 0
	v_add_f32_e32 v130, v130, v131
	v_fmamk_f32 v130, v130, 0x3b800000, v162
	v_cmp_gt_f32_e32 vcc, s26, v130
	v_mul_f32_e32 v131, 0x4b800000, v130
	s_nop 0
	v_cndmask_b32_e32 v130, v130, v131, vcc
	v_rsq_f32_e32 v130, v130
	s_nop 0
	v_mul_f32_e32 v131, 0x45800000, v130
	v_cndmask_b32_e32 v130, v130, v131, vcc
	v_mul_f32_e32 v134, 0x3dd53b94, v130
	v_lshlrev_b64 v[130:131], 8, v[128:129]
	v_lshl_add_u64 v[154:155], v[142:143], 0, v[130:131]
	global_load_dwordx4 v[130:133], v[154:155], off offset:48
	global_load_dwordx4 v[166:169], v[154:155], off offset:32
	global_load_dwordx4 v[170:173], v[154:155], off offset:16
	global_load_dwordx4 v[174:177], v[154:155], off
	v_mad_i64_i32 v[128:129], s[30:31], v128, 6, s[66:67]
	s_waitcnt vmcnt(0)
	v_mov_b32_e32 v154, v175
	v_mov_b32_e32 v155, v177
	v_pk_mul_f32 v[178:179], v[28:29], v[154:155]
	v_mov_b32_e32 v175, v176
	v_pk_mul_f32 v[154:155], v[20:21], v[154:155]
	v_pk_fma_f32 v[176:177], v[20:21], v[174:175], v[178:179]
	v_pk_fma_f32 v[154:155], v[28:29], v[174:175], v[154:155] neg_lo:[0,0,1] neg_hi:[0,0,1]
	v_mov_b32_e32 v174, v171
	v_mov_b32_e32 v175, v173
	v_pk_mul_f32 v[178:179], v[30:31], v[174:175]
	v_mov_b32_e32 v171, v172
	v_pk_mul_f32 v[174:175], v[22:23], v[174:175]
	v_pk_fma_f32 v[172:173], v[22:23], v[170:171], v[178:179]
	v_pk_fma_f32 v[170:171], v[30:31], v[170:171], v[174:175] neg_lo:[0,0,1] neg_hi:[0,0,1]
	v_mov_b32_e32 v174, v167
	v_mov_b32_e32 v175, v169
	v_pk_mul_f32 v[178:179], v[24:25], v[174:175]
	v_mov_b32_e32 v167, v168
	v_pk_mul_f32 v[174:175], v[16:17], v[174:175]
	v_pk_fma_f32 v[168:169], v[16:17], v[166:167], v[178:179]
	v_pk_fma_f32 v[166:167], v[24:25], v[166:167], v[174:175] neg_lo:[0,0,1] neg_hi:[0,0,1]
	v_mov_b32_e32 v174, v131
	v_mov_b32_e32 v175, v133
	v_pk_mul_f32 v[178:179], v[26:27], v[174:175]
	v_mov_b32_e32 v131, v132
	v_pk_fma_f32 v[132:133], v[18:19], v[130:131], v[178:179]
	v_pk_mul_f32 v[176:177], v[176:177], v[134:135] op_sel_hi:[1,0]
	v_pk_mul_f32 v[178:179], v[134:135], v[132:133] op_sel_hi:[0,1]
	v_pk_mul_f32 v[132:133], v[18:19], v[174:175]
	v_pk_mul_f32 v[154:155], v[154:155], v[134:135] op_sel_hi:[1,0]
	v_pk_fma_f32 v[130:131], v[26:27], v[130:131], v[132:133] neg_lo:[0,0,1] neg_hi:[0,0,1]
	v_pk_mul_f32 v[172:173], v[172:173], v[134:135] op_sel_hi:[1,0]
	v_pk_mul_f32 v[170:171], v[170:171], v[134:135] op_sel_hi:[1,0]
	v_pk_mul_f32 v[168:169], v[134:135], v[168:169] op_sel_hi:[0,1]
	v_pk_mul_f32 v[166:167], v[134:135], v[166:167] op_sel_hi:[0,1]
	v_pk_mul_f32 v[134:135], v[134:135], v[130:131] op_sel_hi:[0,1]
	v_cvt_pk_bf16_f32 v130, v154, v155
	v_cvt_pk_bf16_f32 v133, v134, v135
	v_mad_u64_u32 v[134:135], s[30:31], v128, s6, v[146:147]
	v_add_u32_e32 v154, 0xb0, v152
	v_cvt_pk_bf16_f32 v131, v170, v171
	v_cvt_pk_bf16_f32 v132, v166, v167
	v_mad_i32_i24 v135, v129, s6, v135
	v_ashrrev_i32_e32 v155, 31, v154
	v_cvt_pk_bf16_f32 v166, v176, v177
	v_cvt_pk_bf16_f32 v167, v172, v173
	v_cvt_pk_bf16_f32 v168, v168, v169
	v_cvt_pk_bf16_f32 v169, v178, v179
	global_store_dwordx4 v[134:135], v[130:133], off offset:256 sc0 sc1
	global_store_dwordx4 v[134:135], v[166:169], off offset:320 sc0 sc1
	v_lshl_add_u64 v[128:129], v[154:155], 4, s[20:21]
	global_load_dwordx4 v[128:131], v[128:129], off
	s_waitcnt vmcnt(0)
	v_mov_b32_e32 v132, v129
	v_mov_b32_e32 v133, v130
	v_mov_b32_e32 v129, v131
	v_pk_add_f32 v[128:129], v[132:133], v[128:129]
	s_nop 0
	v_add_f32_e32 v128, v128, v129
	v_fmamk_f32 v128, v128, 0x3b800000, v162
	v_cmp_gt_f32_e32 vcc, s26, v128
	v_mul_f32_e32 v129, 0x4b800000, v128
	s_nop 0
	v_cndmask_b32_e32 v128, v128, v129, vcc
	v_rsq_f32_e32 v128, v128
	s_nop 0
	v_mul_f32_e32 v129, 0x45800000, v128
	v_cndmask_b32_e32 v128, v128, v129, vcc
	v_mul_f32_e32 v174, 0x3dd53b94, v128
	v_lshlrev_b64 v[128:129], 8, v[154:155]
	v_lshl_add_u64 v[170:171], v[142:143], 0, v[128:129]
	global_load_dwordx4 v[128:131], v[170:171], off offset:48
	global_load_dwordx4 v[132:135], v[170:171], off offset:32
	global_load_dwordx4 v[166:169], v[170:171], off offset:16
	s_nop 0
	global_load_dwordx4 v[170:173], v[170:171], off
	v_mad_i64_i32 v[154:155], s[30:31], v154, 6, s[66:67]
	s_waitcnt vmcnt(0)
	v_mov_b32_e32 v176, v171
	v_mov_b32_e32 v177, v173
	v_pk_mul_f32 v[178:179], v[12:13], v[176:177]
	v_mov_b32_e32 v171, v172
	v_pk_mul_f32 v[176:177], v[4:5], v[176:177]
	v_pk_fma_f32 v[172:173], v[4:5], v[170:171], v[178:179]
	v_pk_fma_f32 v[170:171], v[12:13], v[170:171], v[176:177] neg_lo:[0,0,1] neg_hi:[0,0,1]
	v_mov_b32_e32 v176, v167
	v_mov_b32_e32 v177, v169
	v_pk_mul_f32 v[178:179], v[14:15], v[176:177]
	v_mov_b32_e32 v167, v168
	v_pk_mul_f32 v[176:177], v[6:7], v[176:177]
	v_pk_fma_f32 v[168:169], v[6:7], v[166:167], v[178:179]
	v_pk_fma_f32 v[166:167], v[14:15], v[166:167], v[176:177] neg_lo:[0,0,1] neg_hi:[0,0,1]
	v_mov_b32_e32 v176, v133
	v_mov_b32_e32 v177, v135
	v_pk_mul_f32 v[178:179], v[8:9], v[176:177]
	v_mov_b32_e32 v133, v134
	v_pk_mul_f32 v[176:177], v[0:1], v[176:177]
	v_pk_fma_f32 v[134:135], v[0:1], v[132:133], v[178:179]
	v_pk_fma_f32 v[132:133], v[8:9], v[132:133], v[176:177] neg_lo:[0,0,1] neg_hi:[0,0,1]
	v_mov_b32_e32 v176, v129
	v_mov_b32_e32 v177, v131
	v_pk_mul_f32 v[178:179], v[10:11], v[176:177]
	v_mov_b32_e32 v129, v130
	v_pk_fma_f32 v[130:131], v[2:3], v[128:129], v[178:179]
	v_pk_mul_f32 v[166:167], v[166:167], v[174:175] op_sel_hi:[1,0]
	v_pk_mul_f32 v[178:179], v[174:175], v[130:131] op_sel_hi:[0,1]
	v_pk_mul_f32 v[130:131], v[2:3], v[176:177]
	v_pk_mul_f32 v[172:173], v[172:173], v[174:175] op_sel_hi:[1,0]
	v_pk_fma_f32 v[128:129], v[10:11], v[128:129], v[130:131] neg_lo:[0,0,1] neg_hi:[0,0,1]
	v_pk_mul_f32 v[170:171], v[170:171], v[174:175] op_sel_hi:[1,0]
	v_pk_mul_f32 v[168:169], v[168:169], v[174:175] op_sel_hi:[1,0]
	v_pk_mul_f32 v[134:135], v[174:175], v[134:135] op_sel_hi:[0,1]
	v_pk_mul_f32 v[132:133], v[174:175], v[132:133] op_sel_hi:[0,1]
	v_pk_mul_f32 v[174:175], v[174:175], v[128:129] op_sel_hi:[0,1]
	v_cvt_pk_bf16_f32 v129, v166, v167
	v_mad_u64_u32 v[166:167], s[30:31], v154, s6, v[146:147]
	v_cvt_pk_bf16_f32 v128, v170, v171
	v_cvt_pk_bf16_f32 v130, v132, v133
	v_cvt_pk_bf16_f32 v131, v174, v175
	v_mad_i32_i24 v167, v155, s6, v167
	v_cvt_pk_bf16_f32 v132, v172, v173
	v_cvt_pk_bf16_f32 v133, v168, v169
	v_cvt_pk_bf16_f32 v134, v134, v135
	v_cvt_pk_bf16_f32 v135, v178, v179
	global_store_dwordx4 v[166:167], v[128:131], off offset:256 sc0 sc1
	global_store_dwordx4 v[166:167], v[132:135], off offset:320 sc0 sc1

.LBB0_1313:
	v_ashrrev_i32_e32 v153, 31, v152
	v_lshl_add_u64 v[132:133], v[152:153], 4, s[20:21]
	global_load_dwordx4 v[128:131], v[132:133], off
	s_lshl_b32 s30, s42, 1
	s_ashr_i32 s31, s30, 31
	s_or_b32 s42, s30, 1
	s_ashr_i32 s43, s42, 31
	s_waitcnt vmcnt(0)
	v_mov_b32_e32 v134, v129
	v_mov_b32_e32 v135, v130
	v_mov_b32_e32 v129, v131
	v_pk_add_f32 v[128:129], v[134:135], v[128:129]
	s_nop 0
	v_add_f32_e32 v128, v128, v129
	v_fmamk_f32 v128, v128, 0x3b800000, v162
	v_cmp_gt_f32_e32 vcc, s26, v128
	v_mul_f32_e32 v129, 0x4b800000, v128
	s_nop 0
	v_cndmask_b32_e32 v128, v128, v129, vcc
	v_rsq_f32_e32 v128, v128
	s_nop 0
	v_mul_f32_e32 v129, 0x45800000, v128
	v_cndmask_b32_e32 v128, v128, v129, vcc
	v_mul_f32_e32 v128, 0x3dd53b94, v128
	v_pk_mul_f32 v[122:123], v[122:123], v[128:129] op_sel_hi:[1,0]
	v_pk_mul_f32 v[120:121], v[120:121], v[128:129] op_sel_hi:[1,0]
	v_pk_mul_f32 v[124:125], v[124:125], v[128:129] op_sel_hi:[1,0]
	v_pk_mul_f32 v[126:127], v[126:127], v[128:129] op_sel_hi:[1,0]
	v_cvt_pk_bf16_f32 v120, v120, v121
	v_cvt_pk_bf16_f32 v121, v122, v123
	v_cvt_pk_bf16_f32 v122, v124, v125
	v_mad_i64_i32 v[124:125], s[34:35], v152, 6, s[30:31]
	v_cvt_pk_bf16_f32 v123, v126, v127
	v_mad_u64_u32 v[126:127], s[34:35], v124, s6, v[144:145]
	v_mad_i32_i24 v127, v125, s6, v127
	global_store_dwordx4 v[126:127], v[120:123], off sc0 sc1
	global_load_dwordx4 v[120:123], v[132:133], off
	s_waitcnt vmcnt(0)
	v_mov_b32_e32 v124, v121
	v_mov_b32_e32 v125, v122
	v_mov_b32_e32 v121, v123
	v_pk_add_f32 v[120:121], v[124:125], v[120:121]
	s_nop 0
	v_add_f32_e32 v120, v120, v121
	v_fmamk_f32 v120, v120, 0x3b800000, v162
	v_cmp_gt_f32_e32 vcc, s26, v120
	v_mul_f32_e32 v121, 0x4b800000, v120
	s_nop 0
	v_cndmask_b32_e32 v120, v120, v121, vcc
	v_rsq_f32_e32 v120, v120
	s_nop 0
	v_mul_f32_e32 v121, 0x45800000, v120
	v_cndmask_b32_e32 v120, v120, v121, vcc
	v_mul_f32_e32 v120, 0x3dd53b94, v120
	v_pk_mul_f32 v[116:117], v[116:117], v[120:121] op_sel_hi:[1,0]
	v_pk_mul_f32 v[118:119], v[118:119], v[120:121] op_sel_hi:[1,0]
	v_pk_mul_f32 v[122:123], v[114:115], v[120:121] op_sel_hi:[1,0]
	v_pk_mul_f32 v[114:115], v[112:113], v[120:121] op_sel_hi:[1,0]
	v_cvt_pk_bf16_f32 v112, v116, v117
	v_mad_i64_i32 v[116:117], s[34:35], v152, 6, s[42:43]
	v_cvt_pk_bf16_f32 v113, v118, v119
	v_mad_u64_u32 v[118:119], s[34:35], v116, s6, v[144:145]
	v_cvt_pk_bf16_f32 v114, v114, v115
	v_cvt_pk_bf16_f32 v115, v122, v123
	v_mad_i32_i24 v119, v117, s6, v119
	global_store_dwordx4 v[118:119], v[112:115], off sc0 sc1
	s_nop 1
	v_or_b32_e32 v112, 16, v152
	v_ashrrev_i32_e32 v113, 31, v112
	v_lshl_add_u64 v[114:115], v[112:113], 4, s[20:21]
	global_load_dwordx4 v[116:119], v[114:115], off
	s_waitcnt vmcnt(0)
	v_mov_b32_e32 v120, v117
	v_mov_b32_e32 v121, v118
	v_mov_b32_e32 v117, v119
	v_pk_add_f32 v[116:117], v[120:121], v[116:117]
	s_nop 0
	v_add_f32_e32 v113, v116, v117
	v_fmamk_f32 v113, v113, 0x3b800000, v162
	v_cmp_gt_f32_e32 vcc, s26, v113
	v_mul_f32_e32 v116, 0x4b800000, v113
	s_nop 0
	v_cndmask_b32_e32 v113, v113, v116, vcc
	v_rsq_f32_e32 v113, v113
	s_nop 0
	v_mul_f32_e32 v116, 0x45800000, v113
	v_cndmask_b32_e32 v113, v113, v116, vcc
	v_mul_f32_e32 v116, 0x3dd53b94, v113
	v_pk_mul_f32 v[108:109], v[108:109], v[116:117] op_sel_hi:[1,0]
	v_pk_mul_f32 v[110:111], v[110:111], v[116:117] op_sel_hi:[1,0]
	v_pk_mul_f32 v[118:119], v[106:107], v[116:117] op_sel_hi:[1,0]
	v_pk_mul_f32 v[106:107], v[104:105], v[116:117] op_sel_hi:[1,0]
	v_cvt_pk_bf16_f32 v104, v108, v109
	v_mad_i64_i32 v[108:109], s[34:35], v112, 6, s[30:31]
	v_cvt_pk_bf16_f32 v105, v110, v111
	v_mad_u64_u32 v[110:111], s[34:35], v108, s6, v[144:145]
	v_cvt_pk_bf16_f32 v106, v106, v107
	v_cvt_pk_bf16_f32 v107, v118, v119
	v_mad_i32_i24 v111, v109, s6, v111
	global_store_dwordx4 v[110:111], v[104:107], off sc0 sc1
	global_load_dwordx4 v[104:107], v[114:115], off
	s_waitcnt vmcnt(0)
	v_mov_b32_e32 v108, v105
	v_mov_b32_e32 v109, v106
	v_mov_b32_e32 v105, v107
	v_pk_add_f32 v[104:105], v[108:109], v[104:105]
	s_nop 0
	v_add_f32_e32 v104, v104, v105
	v_fmamk_f32 v104, v104, 0x3b800000, v162
	v_cmp_gt_f32_e32 vcc, s26, v104
	v_mul_f32_e32 v105, 0x4b800000, v104
	s_nop 0
	v_cndmask_b32_e32 v104, v104, v105, vcc
	v_rsq_f32_e32 v104, v104
	s_nop 0
	v_mul_f32_e32 v105, 0x45800000, v104
	v_cndmask_b32_e32 v104, v104, v105, vcc
	v_mul_f32_e32 v104, 0x3dd53b94, v104
	v_pk_mul_f32 v[100:101], v[100:101], v[104:105] op_sel_hi:[1,0]
	v_pk_mul_f32 v[102:103], v[102:103], v[104:105] op_sel_hi:[1,0]
	v_pk_mul_f32 v[106:107], v[98:99], v[104:105] op_sel_hi:[1,0]
	v_pk_mul_f32 v[98:99], v[96:97], v[104:105] op_sel_hi:[1,0]
	v_cvt_pk_bf16_f32 v96, v100, v101
	v_mad_i64_i32 v[100:101], s[34:35], v112, 6, s[42:43]
	v_cvt_pk_bf16_f32 v97, v102, v103
	v_mad_u64_u32 v[102:103], s[34:35], v100, s6, v[144:145]
	v_cvt_pk_bf16_f32 v98, v98, v99
	v_cvt_pk_bf16_f32 v99, v106, v107
	v_mad_i32_i24 v103, v101, s6, v103
	global_store_dwordx4 v[102:103], v[96:99], off sc0 sc1
	s_nop 1
	v_or_b32_e32 v96, 32, v152
	v_ashrrev_i32_e32 v97, 31, v96
	v_lshl_add_u64 v[98:99], v[96:97], 4, s[20:21]
	global_load_dwordx4 v[100:103], v[98:99], off
	s_waitcnt vmcnt(0)
	v_mov_b32_e32 v104, v101
	v_mov_b32_e32 v105, v102
	v_mov_b32_e32 v101, v103
	v_pk_add_f32 v[100:101], v[104:105], v[100:101]
	s_nop 0
	v_add_f32_e32 v97, v100, v101
	v_fmamk_f32 v97, v97, 0x3b800000, v162
	v_cmp_gt_f32_e32 vcc, s26, v97
	v_mul_f32_e32 v100, 0x4b800000, v97
	s_nop 0
	v_cndmask_b32_e32 v97, v97, v100, vcc
	v_rsq_f32_e32 v97, v97
	s_nop 0
	v_mul_f32_e32 v100, 0x45800000, v97
	v_cndmask_b32_e32 v97, v97, v100, vcc
	v_mul_f32_e32 v100, 0x3dd53b94, v97
	v_pk_mul_f32 v[92:93], v[92:93], v[100:101] op_sel_hi:[1,0]
	v_pk_mul_f32 v[94:95], v[94:95], v[100:101] op_sel_hi:[1,0]
	v_pk_mul_f32 v[102:103], v[90:91], v[100:101] op_sel_hi:[1,0]
	v_pk_mul_f32 v[90:91], v[88:89], v[100:101] op_sel_hi:[1,0]
	v_cvt_pk_bf16_f32 v88, v92, v93
	v_mad_i64_i32 v[92:93], s[34:35], v96, 6, s[30:31]
	v_cvt_pk_bf16_f32 v89, v94, v95
	v_mad_u64_u32 v[94:95], s[34:35], v92, s6, v[144:145]
	v_cvt_pk_bf16_f32 v90, v90, v91
	v_cvt_pk_bf16_f32 v91, v102, v103
	v_mad_i32_i24 v95, v93, s6, v95
	global_store_dwordx4 v[94:95], v[88:91], off sc0 sc1
	global_load_dwordx4 v[88:91], v[98:99], off
	s_waitcnt vmcnt(0)
	v_mov_b32_e32 v92, v89
	v_mov_b32_e32 v93, v90
	v_mov_b32_e32 v89, v91
	v_pk_add_f32 v[88:89], v[92:93], v[88:89]
	s_nop 0
	v_add_f32_e32 v88, v88, v89
	v_fmamk_f32 v88, v88, 0x3b800000, v162
	v_cmp_gt_f32_e32 vcc, s26, v88
	v_mul_f32_e32 v89, 0x4b800000, v88
	s_nop 0
	v_cndmask_b32_e32 v88, v88, v89, vcc
	v_rsq_f32_e32 v88, v88
	s_nop 0
	v_mul_f32_e32 v89, 0x45800000, v88
	v_cndmask_b32_e32 v88, v88, v89, vcc
	v_mul_f32_e32 v88, 0x3dd53b94, v88
	v_pk_mul_f32 v[84:85], v[84:85], v[88:89] op_sel_hi:[1,0]
	v_pk_mul_f32 v[86:87], v[86:87], v[88:89] op_sel_hi:[1,0]
	v_pk_mul_f32 v[90:91], v[82:83], v[88:89] op_sel_hi:[1,0]
	v_pk_mul_f32 v[82:83], v[80:81], v[88:89] op_sel_hi:[1,0]
	v_cvt_pk_bf16_f32 v80, v84, v85
	v_mad_i64_i32 v[84:85], s[34:35], v96, 6, s[42:43]
	v_cvt_pk_bf16_f32 v81, v86, v87
	v_mad_u64_u32 v[86:87], s[34:35], v84, s6, v[144:145]
	v_cvt_pk_bf16_f32 v82, v82, v83
	v_cvt_pk_bf16_f32 v83, v90, v91
	v_mad_i32_i24 v87, v85, s6, v87
	global_store_dwordx4 v[86:87], v[80:83], off sc0 sc1
	s_nop 1
	v_or_b32_e32 v80, 48, v152
	v_ashrrev_i32_e32 v81, 31, v80
	v_lshl_add_u64 v[82:83], v[80:81], 4, s[20:21]
	global_load_dwordx4 v[84:87], v[82:83], off
	s_waitcnt vmcnt(0)
	v_mov_b32_e32 v88, v85
	v_mov_b32_e32 v89, v86
	v_mov_b32_e32 v85, v87
	v_pk_add_f32 v[84:85], v[88:89], v[84:85]
	s_nop 0
	v_add_f32_e32 v81, v84, v85
	v_fmamk_f32 v81, v81, 0x3b800000, v162
	v_cmp_gt_f32_e32 vcc, s26, v81
	v_mul_f32_e32 v84, 0x4b800000, v81
	s_nop 0
	v_cndmask_b32_e32 v81, v81, v84, vcc
	v_rsq_f32_e32 v81, v81
	s_nop 0
	v_mul_f32_e32 v84, 0x45800000, v81
	v_cndmask_b32_e32 v81, v81, v84, vcc
	v_mul_f32_e32 v84, 0x3dd53b94, v81
	v_pk_mul_f32 v[76:77], v[76:77], v[84:85] op_sel_hi:[1,0]
	v_pk_mul_f32 v[78:79], v[78:79], v[84:85] op_sel_hi:[1,0]
	v_pk_mul_f32 v[86:87], v[74:75], v[84:85] op_sel_hi:[1,0]
	v_pk_mul_f32 v[74:75], v[72:73], v[84:85] op_sel_hi:[1,0]
	v_cvt_pk_bf16_f32 v72, v76, v77
	v_mad_i64_i32 v[76:77], s[34:35], v80, 6, s[30:31]
	v_cvt_pk_bf16_f32 v73, v78, v79
	v_mad_u64_u32 v[78:79], s[34:35], v76, s6, v[144:145]
	v_cvt_pk_bf16_f32 v74, v74, v75
	v_cvt_pk_bf16_f32 v75, v86, v87
	v_mad_i32_i24 v79, v77, s6, v79
	global_store_dwordx4 v[78:79], v[72:75], off sc0 sc1
	global_load_dwordx4 v[72:75], v[82:83], off
	s_waitcnt vmcnt(0)
	v_mov_b32_e32 v76, v73
	v_mov_b32_e32 v77, v74
	v_mov_b32_e32 v73, v75
	v_pk_add_f32 v[72:73], v[76:77], v[72:73]
	s_nop 0
	v_add_f32_e32 v72, v72, v73
	v_fmamk_f32 v72, v72, 0x3b800000, v162
	v_cmp_gt_f32_e32 vcc, s26, v72
	v_mul_f32_e32 v73, 0x4b800000, v72
	s_nop 0
	v_cndmask_b32_e32 v72, v72, v73, vcc
	v_rsq_f32_e32 v72, v72
	s_nop 0
	v_mul_f32_e32 v73, 0x45800000, v72
	v_cndmask_b32_e32 v72, v72, v73, vcc
	v_mul_f32_e32 v72, 0x3dd53b94, v72
	v_pk_mul_f32 v[68:69], v[68:69], v[72:73] op_sel_hi:[1,0]
	v_pk_mul_f32 v[70:71], v[70:71], v[72:73] op_sel_hi:[1,0]
	v_pk_mul_f32 v[74:75], v[66:67], v[72:73] op_sel_hi:[1,0]
	v_pk_mul_f32 v[66:67], v[64:65], v[72:73] op_sel_hi:[1,0]
	v_cvt_pk_bf16_f32 v64, v68, v69
	v_mad_i64_i32 v[68:69], s[34:35], v80, 6, s[42:43]
	v_cvt_pk_bf16_f32 v65, v70, v71
	v_mad_u64_u32 v[70:71], s[34:35], v68, s6, v[144:145]
	v_cvt_pk_bf16_f32 v66, v66, v67
	v_cvt_pk_bf16_f32 v67, v74, v75
	v_mad_i32_i24 v71, v69, s6, v71
	global_store_dwordx4 v[70:71], v[64:67], off sc0 sc1
	s_nop 1
	v_add_u32_e32 v64, 0x80, v152
	v_ashrrev_i32_e32 v65, 31, v64
	v_lshl_add_u64 v[66:67], v[64:65], 4, s[20:21]
	global_load_dwordx4 v[68:71], v[66:67], off
	s_waitcnt vmcnt(0)
	v_mov_b32_e32 v72, v69
	v_mov_b32_e32 v73, v70
	v_mov_b32_e32 v69, v71
	v_pk_add_f32 v[68:69], v[72:73], v[68:69]
	s_nop 0
	v_add_f32_e32 v65, v68, v69
	v_fmamk_f32 v65, v65, 0x3b800000, v162
	v_cmp_gt_f32_e32 vcc, s26, v65
	v_mul_f32_e32 v68, 0x4b800000, v65
	s_nop 0
	v_cndmask_b32_e32 v65, v65, v68, vcc
	v_rsq_f32_e32 v65, v65
	s_nop 0
	v_mul_f32_e32 v68, 0x45800000, v65
	v_cndmask_b32_e32 v65, v65, v68, vcc
	v_mul_f32_e32 v68, 0x3dd53b94, v65
	v_pk_mul_f32 v[60:61], v[60:61], v[68:69] op_sel_hi:[1,0]
	v_pk_mul_f32 v[62:63], v[62:63], v[68:69] op_sel_hi:[1,0]
	v_pk_mul_f32 v[70:71], v[58:59], v[68:69] op_sel_hi:[1,0]
	v_pk_mul_f32 v[58:59], v[56:57], v[68:69] op_sel_hi:[1,0]
	v_cvt_pk_bf16_f32 v56, v60, v61
	v_mad_i64_i32 v[60:61], s[34:35], v64, 6, s[30:31]
	v_cvt_pk_bf16_f32 v57, v62, v63
	v_mad_u64_u32 v[62:63], s[34:35], v60, s6, v[144:145]
	v_cvt_pk_bf16_f32 v58, v58, v59
	v_cvt_pk_bf16_f32 v59, v70, v71
	v_mad_i32_i24 v63, v61, s6, v63
	global_store_dwordx4 v[62:63], v[56:59], off sc0 sc1
	global_load_dwordx4 v[56:59], v[66:67], off
	s_waitcnt vmcnt(0)
	v_mov_b32_e32 v60, v57
	v_mov_b32_e32 v61, v58
	v_mov_b32_e32 v57, v59
	v_pk_add_f32 v[56:57], v[60:61], v[56:57]
	s_nop 0
	v_add_f32_e32 v56, v56, v57
	v_fmamk_f32 v56, v56, 0x3b800000, v162
	v_cmp_gt_f32_e32 vcc, s26, v56
	v_mul_f32_e32 v57, 0x4b800000, v56
	s_nop 0
	v_cndmask_b32_e32 v56, v56, v57, vcc
	v_rsq_f32_e32 v56, v56
	s_nop 0
	v_mul_f32_e32 v57, 0x45800000, v56
	v_cndmask_b32_e32 v56, v56, v57, vcc
	v_mul_f32_e32 v56, 0x3dd53b94, v56
	v_pk_mul_f32 v[52:53], v[52:53], v[56:57] op_sel_hi:[1,0]
	v_pk_mul_f32 v[54:55], v[54:55], v[56:57] op_sel_hi:[1,0]
	v_pk_mul_f32 v[58:59], v[50:51], v[56:57] op_sel_hi:[1,0]
	v_pk_mul_f32 v[50:51], v[48:49], v[56:57] op_sel_hi:[1,0]
	v_cvt_pk_bf16_f32 v48, v52, v53
	v_mad_i64_i32 v[52:53], s[34:35], v64, 6, s[42:43]
	v_cvt_pk_bf16_f32 v49, v54, v55
	v_mad_u64_u32 v[54:55], s[34:35], v52, s6, v[144:145]
	v_cvt_pk_bf16_f32 v50, v50, v51
	v_cvt_pk_bf16_f32 v51, v58, v59
	v_mad_i32_i24 v55, v53, s6, v55
	global_store_dwordx4 v[54:55], v[48:51], off sc0 sc1
	s_nop 1
	v_add_u32_e32 v48, 0x90, v152
	v_ashrrev_i32_e32 v49, 31, v48
	v_lshl_add_u64 v[50:51], v[48:49], 4, s[20:21]
	global_load_dwordx4 v[52:55], v[50:51], off
	s_waitcnt vmcnt(0)
	v_mov_b32_e32 v56, v53
	v_mov_b32_e32 v57, v54
	v_mov_b32_e32 v53, v55
	v_pk_add_f32 v[52:53], v[56:57], v[52:53]
	s_nop 0
	v_add_f32_e32 v49, v52, v53
	v_fmamk_f32 v49, v49, 0x3b800000, v162
	v_cmp_gt_f32_e32 vcc, s26, v49
	v_mul_f32_e32 v52, 0x4b800000, v49
	s_nop 0
	v_cndmask_b32_e32 v49, v49, v52, vcc
	v_rsq_f32_e32 v49, v49
	s_nop 0
	v_mul_f32_e32 v52, 0x45800000, v49
	v_cndmask_b32_e32 v49, v49, v52, vcc
	v_mul_f32_e32 v52, 0x3dd53b94, v49
	v_pk_mul_f32 v[44:45], v[44:45], v[52:53] op_sel_hi:[1,0]
	v_pk_mul_f32 v[46:47], v[46:47], v[52:53] op_sel_hi:[1,0]
	v_pk_mul_f32 v[54:55], v[42:43], v[52:53] op_sel_hi:[1,0]
	v_pk_mul_f32 v[42:43], v[40:41], v[52:53] op_sel_hi:[1,0]
	v_cvt_pk_bf16_f32 v40, v44, v45
	v_mad_i64_i32 v[44:45], s[34:35], v48, 6, s[30:31]
	v_cvt_pk_bf16_f32 v41, v46, v47
	v_mad_u64_u32 v[46:47], s[34:35], v44, s6, v[144:145]
	v_cvt_pk_bf16_f32 v42, v42, v43
	v_cvt_pk_bf16_f32 v43, v54, v55
	v_mad_i32_i24 v47, v45, s6, v47
	global_store_dwordx4 v[46:47], v[40:43], off sc0 sc1
	global_load_dwordx4 v[40:43], v[50:51], off
	s_waitcnt vmcnt(0)
	v_mov_b32_e32 v44, v41
	v_mov_b32_e32 v45, v42
	v_mov_b32_e32 v41, v43
	v_pk_add_f32 v[40:41], v[44:45], v[40:41]
	s_nop 0
	v_add_f32_e32 v40, v40, v41
	v_fmamk_f32 v40, v40, 0x3b800000, v162
	v_cmp_gt_f32_e32 vcc, s26, v40
	v_mul_f32_e32 v41, 0x4b800000, v40
	s_nop 0
	v_cndmask_b32_e32 v40, v40, v41, vcc
	v_rsq_f32_e32 v40, v40
	s_nop 0
	v_mul_f32_e32 v41, 0x45800000, v40
	v_cndmask_b32_e32 v40, v40, v41, vcc
	v_mul_f32_e32 v40, 0x3dd53b94, v40
	v_pk_mul_f32 v[36:37], v[36:37], v[40:41] op_sel_hi:[1,0]
	v_pk_mul_f32 v[38:39], v[38:39], v[40:41] op_sel_hi:[1,0]
	v_pk_mul_f32 v[42:43], v[34:35], v[40:41] op_sel_hi:[1,0]
	v_pk_mul_f32 v[34:35], v[32:33], v[40:41] op_sel_hi:[1,0]
	v_cvt_pk_bf16_f32 v32, v36, v37
	v_mad_i64_i32 v[36:37], s[34:35], v48, 6, s[42:43]
	v_cvt_pk_bf16_f32 v33, v38, v39
	v_mad_u64_u32 v[38:39], s[34:35], v36, s6, v[144:145]
	v_cvt_pk_bf16_f32 v34, v34, v35
	v_cvt_pk_bf16_f32 v35, v42, v43
	v_mad_i32_i24 v39, v37, s6, v39
	global_store_dwordx4 v[38:39], v[32:35], off sc0 sc1
	s_nop 1
	v_add_u32_e32 v32, 0xa0, v152
	v_ashrrev_i32_e32 v33, 31, v32
	v_lshl_add_u64 v[34:35], v[32:33], 4, s[20:21]
	global_load_dwordx4 v[36:39], v[34:35], off
	s_waitcnt vmcnt(0)
	v_mov_b32_e32 v40, v37
	v_mov_b32_e32 v41, v38
	v_mov_b32_e32 v37, v39
	v_pk_add_f32 v[36:37], v[40:41], v[36:37]
	s_nop 0
	v_add_f32_e32 v33, v36, v37
	v_fmamk_f32 v33, v33, 0x3b800000, v162
	v_cmp_gt_f32_e32 vcc, s26, v33
	v_mul_f32_e32 v36, 0x4b800000, v33
	s_nop 0
	v_cndmask_b32_e32 v33, v33, v36, vcc
	v_rsq_f32_e32 v33, v33
	s_nop 0
	v_mul_f32_e32 v36, 0x45800000, v33
	v_cndmask_b32_e32 v33, v33, v36, vcc
	v_mul_f32_e32 v36, 0x3dd53b94, v33
	v_pk_mul_f32 v[28:29], v[28:29], v[36:37] op_sel_hi:[1,0]
	v_pk_mul_f32 v[30:31], v[30:31], v[36:37] op_sel_hi:[1,0]
	v_pk_mul_f32 v[38:39], v[26:27], v[36:37] op_sel_hi:[1,0]
	v_pk_mul_f32 v[26:27], v[24:25], v[36:37] op_sel_hi:[1,0]
	v_cvt_pk_bf16_f32 v24, v28, v29
	v_mad_i64_i32 v[28:29], s[34:35], v32, 6, s[30:31]
	v_cvt_pk_bf16_f32 v25, v30, v31
	v_mad_u64_u32 v[30:31], s[34:35], v28, s6, v[144:145]
	v_cvt_pk_bf16_f32 v26, v26, v27
	v_cvt_pk_bf16_f32 v27, v38, v39
	v_mad_i32_i24 v31, v29, s6, v31
	global_store_dwordx4 v[30:31], v[24:27], off sc0 sc1
	global_load_dwordx4 v[24:27], v[34:35], off
	s_waitcnt vmcnt(0)
	v_mov_b32_e32 v28, v25
	v_mov_b32_e32 v29, v26
	v_mov_b32_e32 v25, v27
	v_pk_add_f32 v[24:25], v[28:29], v[24:25]
	s_nop 0
	v_add_f32_e32 v24, v24, v25
	v_fmamk_f32 v24, v24, 0x3b800000, v162
	v_cmp_gt_f32_e32 vcc, s26, v24
	v_mul_f32_e32 v25, 0x4b800000, v24
	s_nop 0
	v_cndmask_b32_e32 v24, v24, v25, vcc
	v_rsq_f32_e32 v24, v24
	s_nop 0
	v_mul_f32_e32 v25, 0x45800000, v24
	v_cndmask_b32_e32 v24, v24, v25, vcc
	v_mul_f32_e32 v24, 0x3dd53b94, v24
	v_pk_mul_f32 v[20:21], v[20:21], v[24:25] op_sel_hi:[1,0]
	v_pk_mul_f32 v[22:23], v[22:23], v[24:25] op_sel_hi:[1,0]
	v_pk_mul_f32 v[26:27], v[18:19], v[24:25] op_sel_hi:[1,0]
	v_pk_mul_f32 v[18:19], v[16:17], v[24:25] op_sel_hi:[1,0]
	v_cvt_pk_bf16_f32 v16, v20, v21
	v_mad_i64_i32 v[20:21], s[34:35], v32, 6, s[42:43]
	v_cvt_pk_bf16_f32 v17, v22, v23
	v_mad_u64_u32 v[22:23], s[34:35], v20, s6, v[144:145]
	v_cvt_pk_bf16_f32 v18, v18, v19
	v_cvt_pk_bf16_f32 v19, v26, v27
	v_mad_i32_i24 v23, v21, s6, v23
	global_store_dwordx4 v[22:23], v[16:19], off sc0 sc1
	s_nop 1
	v_add_u32_e32 v16, 0xb0, v152
	v_ashrrev_i32_e32 v17, 31, v16
	v_lshl_add_u64 v[18:19], v[16:17], 4, s[20:21]
	global_load_dwordx4 v[20:23], v[18:19], off
	s_waitcnt vmcnt(0)
	v_mov_b32_e32 v24, v21
	v_mov_b32_e32 v25, v22
	v_mov_b32_e32 v21, v23
	v_pk_add_f32 v[20:21], v[24:25], v[20:21]
	s_nop 0
	v_add_f32_e32 v17, v20, v21
	v_fmamk_f32 v17, v17, 0x3b800000, v162
	v_cmp_gt_f32_e32 vcc, s26, v17
	v_mul_f32_e32 v20, 0x4b800000, v17
	s_nop 0
	v_cndmask_b32_e32 v17, v17, v20, vcc
	v_rsq_f32_e32 v17, v17
	s_nop 0
	v_mul_f32_e32 v20, 0x45800000, v17
	v_cndmask_b32_e32 v17, v17, v20, vcc
	v_mul_f32_e32 v20, 0x3dd53b94, v17
	v_pk_mul_f32 v[12:13], v[12:13], v[20:21] op_sel_hi:[1,0]
	v_pk_mul_f32 v[14:15], v[14:15], v[20:21] op_sel_hi:[1,0]
	v_pk_mul_f32 v[22:23], v[10:11], v[20:21] op_sel_hi:[1,0]
	v_pk_mul_f32 v[10:11], v[8:9], v[20:21] op_sel_hi:[1,0]
	v_cvt_pk_bf16_f32 v8, v12, v13
	v_mad_i64_i32 v[12:13], s[30:31], v16, 6, s[30:31]
	v_cvt_pk_bf16_f32 v9, v14, v15
	v_mad_u64_u32 v[14:15], s[30:31], v12, s6, v[144:145]
	v_cvt_pk_bf16_f32 v10, v10, v11
	v_cvt_pk_bf16_f32 v11, v22, v23
	v_mad_i32_i24 v15, v13, s6, v15
	global_store_dwordx4 v[14:15], v[8:11], off sc0 sc1
	global_load_dwordx4 v[8:11], v[18:19], off
	s_waitcnt vmcnt(0)
	v_mov_b32_e32 v12, v9
	v_mov_b32_e32 v13, v10
	v_mov_b32_e32 v9, v11
	v_pk_add_f32 v[8:9], v[12:13], v[8:9]
	s_nop 0
	v_add_f32_e32 v8, v8, v9
	v_fmamk_f32 v8, v8, 0x3b800000, v162
	v_cmp_gt_f32_e32 vcc, s26, v8
	v_mul_f32_e32 v9, 0x4b800000, v8
	s_nop 0
	v_cndmask_b32_e32 v8, v8, v9, vcc
	v_rsq_f32_e32 v8, v8
	s_nop 0
	v_mul_f32_e32 v9, 0x45800000, v8
	v_cndmask_b32_e32 v8, v8, v9, vcc
	v_mul_f32_e32 v8, 0x3dd53b94, v8
	v_pk_mul_f32 v[4:5], v[4:5], v[8:9] op_sel_hi:[1,0]
	v_pk_mul_f32 v[6:7], v[6:7], v[8:9] op_sel_hi:[1,0]
	v_pk_mul_f32 v[10:11], v[2:3], v[8:9] op_sel_hi:[1,0]
	v_pk_mul_f32 v[2:3], v[0:1], v[8:9] op_sel_hi:[1,0]
	v_cvt_pk_bf16_f32 v0, v4, v5
	v_mad_i64_i32 v[4:5], s[30:31], v16, 6, s[42:43]
	v_cvt_pk_bf16_f32 v1, v6, v7
	v_mad_u64_u32 v[6:7], s[30:31], v4, s6, v[144:145]
	v_cvt_pk_bf16_f32 v2, v2, v3
	v_cvt_pk_bf16_f32 v3, v10, v11
	v_mad_i32_i24 v7, v5, s6, v7
	global_store_dwordx4 v[6:7], v[0:3], off sc0 sc1
	s_and_b64 vcc, exec, s[38:39]
	s_mov_b64 s[30:31], -1
	s_cbranch_vccnz .LBB0_1291

.LBB0_1476:
	v_lshl_or_b32 v132, s82, 8, v192
	v_pk_mul_f32 v[126:127], v[126:127], v[188:189] op_sel_hi:[1,0]
	v_pk_mul_f32 v[124:125], v[124:125], v[188:189] op_sel_hi:[1,0]
	v_pk_mul_f32 v[122:123], v[122:123], v[188:189] op_sel_hi:[1,0]
	v_ashrrev_i32_e32 v133, 31, v132
	v_pk_mul_f32 v[120:121], v[120:121], v[188:189] op_sel_hi:[1,0]
	v_cvt_pk_bf16_f32 v124, v124, v125
	v_cvt_pk_bf16_f32 v125, v126, v127
	v_cvt_pk_bf16_f32 v127, v122, v123
	v_mov_b64_e32 v[122:123], s[22:23]
	s_movk_i32 s2, 0x1c00
	v_cvt_pk_bf16_f32 v126, v120, v121
	v_mad_i64_i32 v[134:135], s[4:5], v184, s2, v[122:123]
	v_lshlrev_b64 v[120:121], 1, v[132:133]
	v_lshl_add_u64 v[132:133], v[134:135], 0, v[120:121]
	global_store_dwordx4 v[132:133], v[124:127], off sc0 sc1
	v_pk_mul_f32 v[118:119], v[118:119], v[188:189] op_sel_hi:[1,0]
	v_pk_mul_f32 v[116:117], v[116:117], v[188:189] op_sel_hi:[1,0]
	v_pk_mul_f32 v[124:125], v[114:115], v[188:189] op_sel_hi:[1,0]
	v_pk_mul_f32 v[114:115], v[112:113], v[188:189] op_sel_hi:[1,0]
	v_cvt_pk_bf16_f32 v112, v116, v117
	v_cvt_pk_bf16_f32 v113, v118, v119
	v_cvt_pk_bf16_f32 v114, v114, v115
	v_cvt_pk_bf16_f32 v115, v124, v125
	v_pk_mul_f32 v[108:109], v[108:109], v[186:187] op_sel_hi:[1,0]
	global_store_dwordx4 v[132:133], v[112:115], off offset:256 sc0 sc1
	v_pk_mul_f32 v[110:111], v[110:111], v[186:187] op_sel_hi:[1,0]
	v_pk_mul_f32 v[102:103], v[102:103], v[186:187] op_sel_hi:[1,0]
	v_pk_mul_f32 v[112:113], v[106:107], v[186:187] op_sel_hi:[1,0]
	v_pk_mul_f32 v[106:107], v[104:105], v[186:187] op_sel_hi:[1,0]
	v_cvt_pk_bf16_f32 v104, v108, v109
	v_mad_u64_u32 v[108:109], s[4:5], v182, s2, v[122:123]
	v_cvt_pk_bf16_f32 v105, v110, v111
	v_mov_b32_e32 v110, v109
	v_mad_u64_u32 v[110:111], s[4:5], v183, s2, v[110:111]
	v_mov_b32_e32 v109, v110
	v_cvt_pk_bf16_f32 v106, v106, v107
	v_cvt_pk_bf16_f32 v107, v112, v113
	v_lshl_add_u64 v[108:109], v[108:109], 0, v[120:121]
	global_store_dwordx4 v[108:109], v[104:107], off sc0 sc1
	v_pk_mul_f32 v[100:101], v[100:101], v[186:187] op_sel_hi:[1,0]
	v_pk_mul_f32 v[92:93], v[92:93], v[146:147] op_sel_hi:[1,0]
	v_pk_mul_f32 v[104:105], v[98:99], v[186:187] op_sel_hi:[1,0]
	v_pk_mul_f32 v[98:99], v[96:97], v[186:187] op_sel_hi:[1,0]
	v_cvt_pk_bf16_f32 v96, v100, v101
	v_cvt_pk_bf16_f32 v97, v102, v103
	v_cvt_pk_bf16_f32 v98, v98, v99
	v_cvt_pk_bf16_f32 v99, v104, v105
	global_store_dwordx4 v[108:109], v[96:99], off offset:256 sc0 sc1
	v_pk_mul_f32 v[94:95], v[94:95], v[146:147] op_sel_hi:[1,0]
	v_pk_mul_f32 v[86:87], v[86:87], v[146:147] op_sel_hi:[1,0]
	v_pk_mul_f32 v[96:97], v[90:91], v[146:147] op_sel_hi:[1,0]
	v_pk_mul_f32 v[90:91], v[88:89], v[146:147] op_sel_hi:[1,0]
	v_cvt_pk_bf16_f32 v88, v92, v93
	v_mad_u64_u32 v[92:93], s[4:5], v180, s2, v[122:123]
	v_cvt_pk_bf16_f32 v89, v94, v95
	v_mov_b32_e32 v94, v93
	v_mad_u64_u32 v[94:95], s[4:5], v181, s2, v[94:95]
	v_mov_b32_e32 v93, v94
	v_cvt_pk_bf16_f32 v90, v90, v91
	v_cvt_pk_bf16_f32 v91, v96, v97
	v_lshl_add_u64 v[92:93], v[92:93], 0, v[120:121]
	global_store_dwordx4 v[92:93], v[88:91], off sc0 sc1
	v_pk_mul_f32 v[84:85], v[84:85], v[146:147] op_sel_hi:[1,0]
	v_pk_mul_f32 v[76:77], v[76:77], v[144:145] op_sel_hi:[1,0]
	v_pk_mul_f32 v[88:89], v[82:83], v[146:147] op_sel_hi:[1,0]
	v_pk_mul_f32 v[82:83], v[80:81], v[146:147] op_sel_hi:[1,0]
	v_cvt_pk_bf16_f32 v80, v84, v85
	v_cvt_pk_bf16_f32 v81, v86, v87
	v_cvt_pk_bf16_f32 v82, v82, v83
	v_cvt_pk_bf16_f32 v83, v88, v89
	global_store_dwordx4 v[92:93], v[80:83], off offset:256 sc0 sc1
	v_pk_mul_f32 v[78:79], v[78:79], v[144:145] op_sel_hi:[1,0]
	v_pk_mul_f32 v[70:71], v[70:71], v[144:145] op_sel_hi:[1,0]
	v_pk_mul_f32 v[80:81], v[74:75], v[144:145] op_sel_hi:[1,0]
	v_pk_mul_f32 v[74:75], v[72:73], v[144:145] op_sel_hi:[1,0]
	v_cvt_pk_bf16_f32 v72, v76, v77
	v_mad_u64_u32 v[76:77], s[4:5], v178, s2, v[122:123]
	v_cvt_pk_bf16_f32 v73, v78, v79
	v_mov_b32_e32 v78, v77
	v_mad_u64_u32 v[78:79], s[4:5], v179, s2, v[78:79]
	v_mov_b32_e32 v77, v78
	v_cvt_pk_bf16_f32 v74, v74, v75
	v_cvt_pk_bf16_f32 v75, v80, v81
	v_lshl_add_u64 v[76:77], v[76:77], 0, v[120:121]
	global_store_dwordx4 v[76:77], v[72:75], off sc0 sc1
	v_pk_mul_f32 v[68:69], v[68:69], v[144:145] op_sel_hi:[1,0]
	v_pk_mul_f32 v[60:61], v[60:61], v[138:139] op_sel_hi:[1,0]
	v_pk_mul_f32 v[72:73], v[66:67], v[144:145] op_sel_hi:[1,0]
	v_pk_mul_f32 v[66:67], v[64:65], v[144:145] op_sel_hi:[1,0]
	v_cvt_pk_bf16_f32 v64, v68, v69
	v_cvt_pk_bf16_f32 v65, v70, v71
	v_cvt_pk_bf16_f32 v66, v66, v67
	v_cvt_pk_bf16_f32 v67, v72, v73
	global_store_dwordx4 v[76:77], v[64:67], off offset:256 sc0 sc1
	v_pk_mul_f32 v[62:63], v[62:63], v[138:139] op_sel_hi:[1,0]
	v_pk_mul_f32 v[54:55], v[54:55], v[138:139] op_sel_hi:[1,0]
	v_pk_mul_f32 v[64:65], v[58:59], v[138:139] op_sel_hi:[1,0]
	v_pk_mul_f32 v[58:59], v[56:57], v[138:139] op_sel_hi:[1,0]
	v_cvt_pk_bf16_f32 v56, v60, v61
	v_mad_u64_u32 v[60:61], s[4:5], v176, s2, v[122:123]
	v_cvt_pk_bf16_f32 v57, v62, v63
	v_mov_b32_e32 v62, v61
	v_mad_u64_u32 v[62:63], s[4:5], v177, s2, v[62:63]
	v_mov_b32_e32 v61, v62
	v_cvt_pk_bf16_f32 v58, v58, v59
	v_cvt_pk_bf16_f32 v59, v64, v65
	v_lshl_add_u64 v[60:61], v[60:61], 0, v[120:121]
	global_store_dwordx4 v[60:61], v[56:59], off sc0 sc1
	v_pk_mul_f32 v[52:53], v[52:53], v[138:139] op_sel_hi:[1,0]
	v_pk_mul_f32 v[44:45], v[44:45], v[136:137] op_sel_hi:[1,0]
	v_pk_mul_f32 v[56:57], v[50:51], v[138:139] op_sel_hi:[1,0]
	v_pk_mul_f32 v[50:51], v[48:49], v[138:139] op_sel_hi:[1,0]
	v_cvt_pk_bf16_f32 v48, v52, v53
	v_cvt_pk_bf16_f32 v49, v54, v55
	v_cvt_pk_bf16_f32 v50, v50, v51
	v_cvt_pk_bf16_f32 v51, v56, v57
	global_store_dwordx4 v[60:61], v[48:51], off offset:256 sc0 sc1
	v_pk_mul_f32 v[46:47], v[46:47], v[136:137] op_sel_hi:[1,0]
	v_pk_mul_f32 v[38:39], v[38:39], v[136:137] op_sel_hi:[1,0]
	v_pk_mul_f32 v[48:49], v[42:43], v[136:137] op_sel_hi:[1,0]
	v_pk_mul_f32 v[42:43], v[40:41], v[136:137] op_sel_hi:[1,0]
	v_cvt_pk_bf16_f32 v40, v44, v45
	v_mad_u64_u32 v[44:45], s[4:5], v174, s2, v[122:123]
	v_cvt_pk_bf16_f32 v41, v46, v47
	v_mov_b32_e32 v46, v45
	v_mad_u64_u32 v[46:47], s[4:5], v175, s2, v[46:47]
	v_mov_b32_e32 v45, v46
	v_cvt_pk_bf16_f32 v42, v42, v43
	v_cvt_pk_bf16_f32 v43, v48, v49
	v_lshl_add_u64 v[44:45], v[44:45], 0, v[120:121]
	global_store_dwordx4 v[44:45], v[40:43], off sc0 sc1
	v_pk_mul_f32 v[36:37], v[36:37], v[136:137] op_sel_hi:[1,0]
	v_pk_mul_f32 v[28:29], v[28:29], v[130:131] op_sel_hi:[1,0]
	v_pk_mul_f32 v[40:41], v[34:35], v[136:137] op_sel_hi:[1,0]
	v_pk_mul_f32 v[34:35], v[32:33], v[136:137] op_sel_hi:[1,0]
	v_cvt_pk_bf16_f32 v32, v36, v37
	v_cvt_pk_bf16_f32 v33, v38, v39
	v_cvt_pk_bf16_f32 v34, v34, v35
	v_cvt_pk_bf16_f32 v35, v40, v41
	global_store_dwordx4 v[44:45], v[32:35], off offset:256 sc0 sc1
	v_pk_mul_f32 v[30:31], v[30:31], v[130:131] op_sel_hi:[1,0]
	v_pk_mul_f32 v[22:23], v[22:23], v[130:131] op_sel_hi:[1,0]
	v_pk_mul_f32 v[32:33], v[26:27], v[130:131] op_sel_hi:[1,0]
	v_pk_mul_f32 v[26:27], v[24:25], v[130:131] op_sel_hi:[1,0]
	v_cvt_pk_bf16_f32 v24, v28, v29
	v_mad_u64_u32 v[28:29], s[4:5], v172, s2, v[122:123]
	v_cvt_pk_bf16_f32 v25, v30, v31
	v_mov_b32_e32 v30, v29
	v_mad_u64_u32 v[30:31], s[4:5], v173, s2, v[30:31]
	v_mov_b32_e32 v29, v30
	v_cvt_pk_bf16_f32 v26, v26, v27
	v_cvt_pk_bf16_f32 v27, v32, v33
	v_lshl_add_u64 v[28:29], v[28:29], 0, v[120:121]
	global_store_dwordx4 v[28:29], v[24:27], off sc0 sc1
	v_pk_mul_f32 v[20:21], v[20:21], v[130:131] op_sel_hi:[1,0]
	v_pk_mul_f32 v[12:13], v[12:13], v[128:129] op_sel_hi:[1,0]
	v_pk_mul_f32 v[24:25], v[18:19], v[130:131] op_sel_hi:[1,0]
	v_pk_mul_f32 v[18:19], v[16:17], v[130:131] op_sel_hi:[1,0]
	v_cvt_pk_bf16_f32 v16, v20, v21
	v_cvt_pk_bf16_f32 v17, v22, v23
	v_cvt_pk_bf16_f32 v18, v18, v19
	v_cvt_pk_bf16_f32 v19, v24, v25
	global_store_dwordx4 v[28:29], v[16:19], off offset:256 sc0 sc1
	v_pk_mul_f32 v[14:15], v[14:15], v[128:129] op_sel_hi:[1,0]
	v_pk_mul_f32 v[6:7], v[6:7], v[128:129] op_sel_hi:[1,0]
	v_pk_mul_f32 v[16:17], v[10:11], v[128:129] op_sel_hi:[1,0]
	v_pk_mul_f32 v[10:11], v[8:9], v[128:129] op_sel_hi:[1,0]
	v_cvt_pk_bf16_f32 v8, v12, v13
	v_mad_u64_u32 v[12:13], s[4:5], v170, s2, v[122:123]
	v_cvt_pk_bf16_f32 v9, v14, v15
	v_mov_b32_e32 v14, v13
	v_mad_u64_u32 v[14:15], s[4:5], v171, s2, v[14:15]
	v_mov_b32_e32 v13, v14
	v_cvt_pk_bf16_f32 v10, v10, v11
	v_cvt_pk_bf16_f32 v11, v16, v17
	v_lshl_add_u64 v[12:13], v[12:13], 0, v[120:121]
	global_store_dwordx4 v[12:13], v[8:11], off sc0 sc1
	v_pk_mul_f32 v[4:5], v[4:5], v[128:129] op_sel_hi:[1,0]
	s_and_b64 vcc, exec, s[38:39]
	v_pk_mul_f32 v[8:9], v[2:3], v[128:129] op_sel_hi:[1,0]
	v_pk_mul_f32 v[2:3], v[0:1], v[128:129] op_sel_hi:[1,0]
	v_cvt_pk_bf16_f32 v0, v4, v5
	v_cvt_pk_bf16_f32 v1, v6, v7
	v_cvt_pk_bf16_f32 v2, v2, v3
	v_cvt_pk_bf16_f32 v3, v8, v9
	s_mov_b64 s[4:5], -1
	global_store_dwordx4 v[12:13], v[0:3], off offset:256 sc0 sc1
	s_cbranch_vccnz .LBB0_1456
	s_andn2_b64 vcc, exec, s[20:21]
	s_cbranch_vccnz .LBB0_1455
	s_barrier
	s_branch .LBB0_1455
